# attention: K DMA before V with vmcnt(2) so V stays in flight one more step; GQA QK LDS reads double-buffered; accumulator zeroing with v_mov_b64
# baseline (speedup 1.0000x reference)
; template <bool MLA>
; __device__ __forceinline__ void qkt(f32x16& p0, f32x16& p1, const char* Ks, const char* KRs, const bf16x8* qr, const char* qrl, const f32x16& negm, int r32, int hi) {
; #pragma unroll
;   for (int d0 = 0; d0 < 8; ++d0) { int cb = (d0 * 16 + hi * 8) * 2;
;     bf16x8 b0 = *reinterpret_cast<const bf16x8*>(Ks + KSWZ(r32, cb));
;     bf16x8 b1 = *reinterpret_cast<const bf16x8*>(Ks + KSWZ(32 + r32, cb));
;     if (d0 == 0) { p0 = __builtin_amdgcn_mfma_f32_32x32x16_bf16(b0, qr[0], negm, 0, 0, 0); p1 = __builtin_amdgcn_mfma_f32_32x32x16_bf16(b1, qr[0], negm, 0, 0, 0); }
;     else { p0 = __builtin_amdgcn_mfma_f32_32x32x16_bf16(b0, qr[d0], p0, 0, 0, 0); p1 = __builtin_amdgcn_mfma_f32_32x32x16_bf16(b1, qr[d0], p1, 0, 0, 0); } }
;   if constexpr (MLA) {
; #pragma unroll
;     for (int d0 = 0; d0 < 4; ++d0) { int ch = d0 * 2 + hi;
;       bf16x8 b0 = *reinterpret_cast<const bf16x8*>(KRs + KRSWZ(r32, ch));
;       bf16x8 b1 = *reinterpret_cast<const bf16x8*>(KRs + KRSWZ(32 + r32, ch));
;       const bf16x8 qq = *reinterpret_cast<const bf16x8*>(qrl + d0 * 1024);
;       p0 = __builtin_amdgcn_mfma_f32_32x32x16_bf16(b0, qq, p0, 0, 0, 0);
;       p1 = __builtin_amdgcn_mfma_f32_32x32x16_bf16(b1, qq, p1, 0, 0, 0); }
;   }
; }
.LBB0_101:
	s_mov_b32 s10, s24
	s_mov_b32 s24, s35
	s_lshl_b32 s2, s25, 14
	s_add_i32 s27, s2, 0
	s_add_i32 s32, s27, s15
	s_lshl_b32 s30, s25, 13
	s_lshl_b32 s11, s10, 14
	s_add_i32 s3, s11, 0
	v_add_u32_e32 v0, s3, v210
	ds_read_b128 v[234:237], v0 offset:57344
	ds_read_b128 v[98:101], v0 offset:49152
	v_add_u32_e32 v0, s3, v209
	s_lshl_b32 s2, s10, 13
	s_add_i32 s2, s2, 0
	s_add_i32 s2, s2, 0x18000
	s_add_u32 vcc_lo, s28, s46
	s_addc_u32 vcc_hi, s29, s47
	s_add_i32 m0, s32, 0xc000
	v_lshl_add_u64 v[250:251], v[172:173], 0, vcc
	global_load_lds_dwordx4 v[250:251], off
	v_exp_f32_e32 v213, v82
	v_add_f32_e32 v212, 0, v227
	v_add_f32_e32 v212, v229, v212
	s_waitcnt lgkmcnt(0)
	v_mfma_f32_32x32x16_bf16 v[114:129], v[98:101], v[158:161], v[66:81]
	v_exp_f32_e32 v246, v83
	v_add_f32_e32 v212, v225, v212
	v_add_f32_e32 v212, v228, v212
	s_lshl_b32 s31, s35, 14
	v_mfma_f32_32x32x16_bf16 v[98:113], v[234:237], v[158:161], v[66:81]
	ds_read_b128 v[234:237], v0 offset:57344
	ds_read_b128 v[238:241], v0 offset:49152
	v_add_u32_e32 v0, s3, v208
	s_add_u32 vcc_lo, s28, s46
	s_addc_u32 vcc_hi, s29, s47
	s_add_i32 m0, s32, 0xc400
	v_lshl_add_u64 v[250:251], v[174:175], 0, vcc
	global_load_lds_dwordx4 v[250:251], off
	v_exp_f32_e32 v247, v84
	v_add_f32_e32 v212, v224, v212
	v_add_f32_e32 v212, v226, v212
	s_waitcnt lgkmcnt(0)
	v_mfma_f32_32x32x16_bf16 v[114:129], v[238:241], v[154:157], v[114:129]
	v_exp_f32_e32 v249, v85
	v_add_f32_e32 v212, v222, v212
	v_add_f32_e32 v212, v223, v212
	v_mfma_f32_32x32x16_bf16 v[98:113], v[234:237], v[154:157], v[98:113]
	ds_read_b128 v[234:237], v0 offset:57344
	ds_read_b128 v[238:241], v0 offset:49152
	v_add_u32_e32 v0, s3, v207
	s_add_u32 vcc_lo, s28, 0x2e340600
	s_addc_u32 vcc_hi, s29, 0
	s_add_i32 m0, s23, s30
	v_lshl_add_u64 v[250:251], v[168:169], 0, vcc
	global_load_lds_dwordx4 v[250:251], off
	v_exp_f32_e32 v252, v86
	v_add_f32_e32 v212, v219, v212
	v_add_f32_e32 v212, v221, v212
	s_waitcnt lgkmcnt(0)
	v_mfma_f32_32x32x16_bf16 v[114:129], v[238:241], v[150:153], v[114:129]
	v_exp_f32_e32 v253, v87
	v_add_f32_e32 v212, v218, v212
	v_add_f32_e32 v212, v220, v212
	v_mfma_f32_32x32x16_bf16 v[98:113], v[234:237], v[150:153], v[98:113]
	ds_read_b128 v[234:237], v0 offset:57344
	ds_read_b128 v[238:241], v0 offset:49152
	v_add_u32_e32 v0, s3, v206
	s_add_u32 vcc_lo, s28, 0x4380100
	s_addc_u32 vcc_hi, s29, 0
	s_mov_b32 m0, s32
	v_lshl_add_u64 v[250:251], v[170:171], 0, vcc
	global_load_lds_dwordx4 v[250:251], off
	v_exp_f32_e32 v254, v88
	v_add_f32_e32 v212, v215, v212
	v_add_f32_e32 v212, v217, v212
	s_waitcnt lgkmcnt(0)
	v_mfma_f32_32x32x16_bf16 v[114:129], v[238:241], v[146:149], v[114:129]
	v_exp_f32_e32 v255, v89
	v_add_f32_e32 v212, v214, v212
	v_add_f32_e32 v212, v216, v212
	v_mfma_f32_32x32x16_bf16 v[98:113], v[234:237], v[146:149], v[98:113]
	ds_read_b128 v[234:237], v0 offset:57344
	ds_read_b128 v[238:241], v0 offset:49152
	v_add_u32_e32 v0, s3, v205
	s_add_u32 vcc_lo, s28, 0x4380180
	s_addc_u32 vcc_hi, s29, 0
	s_add_i32 m0, s32, 0x400
	v_lshl_add_u64 v[250:251], v[170:171], 0, vcc
	global_load_lds_dwordx4 v[250:251], off
	v_cvt_pk_bf16_f32 v82, v227, v229
	v_exp_f32_e32 v90, v90
	v_cvt_pk_bf16_f32 v83, v225, v228
	s_waitcnt lgkmcnt(0)
	v_mfma_f32_32x32x16_bf16 v[114:129], v[238:241], v[142:145], v[114:129]
	v_exp_f32_e32 v91, v91
	v_cvt_pk_bf16_f32 v84, v224, v226
	v_exp_f32_e32 v92, v92
	v_mfma_f32_32x32x16_bf16 v[98:113], v[234:237], v[142:145], v[98:113]
	ds_read_b128 v[234:237], v0 offset:57344
	ds_read_b128 v[238:241], v0 offset:49152
	v_add_u32_e32 v0, s3, v204
	v_cvt_pk_bf16_f32 v85, v222, v223
	v_exp_f32_e32 v93, v93
	v_cvt_pk_bf16_f32 v86, v219, v221
	s_waitcnt lgkmcnt(0)
	v_mfma_f32_32x32x16_bf16 v[114:129], v[238:241], v[138:141], v[114:129]
	v_exp_f32_e32 v94, v94
	v_cvt_pk_bf16_f32 v87, v218, v220
	v_exp_f32_e32 v95, v95
	v_mfma_f32_32x32x16_bf16 v[98:113], v[234:237], v[138:141], v[98:113]
	ds_read_b128 v[234:237], v0 offset:57344
	ds_read_b128 v[238:241], v0 offset:49152
	v_add_u32_e32 v0, s3, v203
	v_cvt_pk_bf16_f32 v88, v215, v217
	v_exp_f32_e32 v96, v96
	v_cvt_pk_bf16_f32 v89, v214, v216
	s_waitcnt lgkmcnt(0)
	v_mfma_f32_32x32x16_bf16 v[114:129], v[238:241], v[134:137], v[114:129]
	v_exp_f32_e32 v97, v97
	v_add_f32_e32 v212, v213, v212
	v_add_f32_e32 v212, v246, v212
	v_mfma_f32_32x32x16_bf16 v[98:113], v[234:237], v[134:137], v[98:113]
	ds_read_b128 v[234:237], v0 offset:57344
	ds_read_b128 v[238:241], v0 offset:49152
	v_add_u32_e32 v0, s2, v200
	v_add_f32_e32 v212, v247, v212
	v_add_f32_e32 v212, v249, v212
	v_add_f32_e32 v212, v252, v212
	s_waitcnt lgkmcnt(0)
	v_mfma_f32_32x32x16_bf16 v[114:129], v[238:241], v[130:133], v[114:129]
	v_add_f32_e32 v212, v253, v212
	v_add_f32_e32 v212, v254, v212
	v_add_f32_e32 v212, v255, v212
	v_mfma_f32_32x32x16_bf16 v[98:113], v[234:237], v[130:133], v[98:113]
	ds_read_b128 v[234:237], v0
	ds_read_b128 v[238:241], v0 offset:4096
	ds_read_b128 v[242:245], v198
	v_add_u32_e32 v0, s2, v201
	v_add_f32_e32 v212, v90, v212
	v_add_f32_e32 v212, v91, v212
	s_waitcnt lgkmcnt(0)
	v_mfma_f32_32x32x16_bf16 v[114:129], v[234:237], v[242:245], v[114:129]
	v_add_f32_e32 v212, v92, v212
	v_add_f32_e32 v212, v93, v212
	v_mfma_f32_32x32x16_bf16 v[98:113], v[238:241], v[242:245], v[98:113]
	ds_read_b128 v[234:237], v0
	ds_read_b128 v[238:241], v0 offset:4096
	ds_read_b128 v[242:245], v198 offset:1024
	v_add_u32_e32 v0, s2, v199
	v_add_f32_e32 v212, v94, v212
	v_add_f32_e32 v212, v95, v212
	s_waitcnt lgkmcnt(0)
; #define SBAR() __builtin_amdgcn_sched_barrier(0)
; __device__ __forceinline__ void finishSM(f32x16& p0, f32x16& p1, float alpha, float& l_reg, bf16x8& pa0, bf16x8& pa1, bf16x8& pa2, bf16x8& pa3) {
; #pragma unroll
;   for (int r = 0; r < 16; ++r) p1[r] = __builtin_amdgcn_exp2f(p1[r]);
;   float ps = 0;
; #pragma unroll
;   for (int r = 0; r < 16; ++r) ps += p0[r];
; #pragma unroll
;   for (int r = 0; r < 16; ++r) ps += p1[r];
;   { auto rr = __builtin_amdgcn_permlane32_swap(__float_as_uint(ps), __float_as_uint(ps), false, false);
;     ps = __uint_as_float(rr[0]) + __uint_as_float(rr[1]); }
;   l_reg = l_reg * alpha + ps;
;     ...
;   PK4(p0, 0, pa0); PK4(p0, 8, pa1); PK4(p1, 0, pa2); PK4(p1, 8, pa3);
;     ...
; }
; template <int D0> __device__ __forceinline__ void pv_one(f32x16& od, int vb, bf16x8 pa0, bf16x8 pa1, bf16x8 pa2, bf16x8 pa3) {
;   const s16x4 l0 = tr_read<v_rd_off(D0, 0, 0)>(vb), h0 = tr_read<v_rd_off(D0, 0, 1)>(vb), l1 = tr_read<v_rd_off(D0, 1, 0)>(vb), h1 = tr_read<v_rd_off(D0, 1, 1)>(vb);
;   const s16x4 l2 = tr_read<v_rd_off(D0, 2, 0)>(vb), h2 = tr_read<v_rd_off(D0, 2, 1)>(vb), l3 = tr_read<v_rd_off(D0, 3, 0)>(vb), h3 = tr_read<v_rd_off(D0, 3, 1)>(vb);
;   asm volatile("s_waitcnt lgkmcnt(0)" ::: "memory"); SBAR();
;     ...
;   od = __builtin_amdgcn_mfma_f32_32x32x16_bf16(pa0, PK(l0, h0), od, 0, 0, 0);
;   od = __builtin_amdgcn_mfma_f32_32x32x16_bf16(pa1, PK(l1, h1), od, 0, 0, 0);
;   od = __builtin_amdgcn_mfma_f32_32x32x16_bf16(pa2, PK(l2, h2), od, 0, 0, 0);
;   od = __builtin_amdgcn_mfma_f32_32x32x16_bf16(pa3, PK(l3, h3), od, 0, 0, 0);
;     ...
; }
	v_mfma_f32_32x32x16_bf16 v[114:129], v[234:237], v[242:245], v[114:129]
	v_add_f32_e32 v212, v96, v212
	v_add_f32_e32 v212, v97, v212
	v_mfma_f32_32x32x16_bf16 v[98:113], v[238:241], v[242:245], v[98:113]
	ds_read_b128 v[234:237], v0
	ds_read_b128 v[238:241], v0 offset:4096
	ds_read_b128 v[242:245], v198 offset:2048
	v_add_u32_e32 v0, s2, v202
	v_cvt_pk_bf16_f32 v97, v96, v97
	v_cvt_pk_bf16_f32 v96, v94, v95
	s_waitcnt lgkmcnt(0)
	v_mfma_f32_32x32x16_bf16 v[114:129], v[234:237], v[242:245], v[114:129]
	v_cvt_pk_bf16_f32 v95, v92, v93
	v_cvt_pk_bf16_f32 v94, v90, v91
	v_mfma_f32_32x32x16_bf16 v[98:113], v[238:241], v[242:245], v[98:113]
	ds_read_b128 v[234:237], v0
	ds_read_b128 v[238:241], v0 offset:4096
	ds_read_b128 v[242:245], v198 offset:3072
	v_cvt_pk_bf16_f32 v90, v213, v246
	v_cvt_pk_bf16_f32 v91, v247, v249
	s_waitcnt lgkmcnt(0)
	v_mfma_f32_32x32x16_bf16 v[114:129], v[234:237], v[242:245], v[114:129]
	v_cvt_pk_bf16_f32 v92, v252, v253
	v_cvt_pk_bf16_f32 v93, v254, v255
	v_mfma_f32_32x32x16_bf16 v[98:113], v[238:241], v[242:245], v[98:113]
	v_add_u32_e32 v213, s31, v197
	ds_read_b64_tr_b16 v[214:215], v213 offset:0
	ds_read_b64_tr_b16 v[216:217], v213 offset:0x800
	ds_read_b64_tr_b16 v[218:219], v213 offset:0x1000
	ds_read_b64_tr_b16 v[220:221], v213 offset:0x1800
	ds_read_b64_tr_b16 v[222:223], v213 offset:0x2000
	ds_read_b64_tr_b16 v[224:225], v213 offset:0x2800
	ds_read_b64_tr_b16 v[226:227], v213 offset:0x3000
	ds_read_b64_tr_b16 v[228:229], v213 offset:0x3800
	s_waitcnt lgkmcnt(0)
	v_mov_b32_e32 v0, v212
	s_nop 1
	v_permlane32_swap_b32_e32 v0, v212
	v_permlane32_swap_b32_e32 v82, v84
	v_permlane32_swap_b32_e32 v83, v85
	v_permlane32_swap_b32_e32 v86, v88
	v_permlane32_swap_b32_e32 v87, v89
	v_permlane32_swap_b32_e32 v90, v92
	v_permlane32_swap_b32_e32 v91, v93
	v_permlane32_swap_b32_e32 v94, v96
	v_permlane32_swap_b32_e32 v95, v97
	v_mfma_f32_32x32x16_bf16 v[50:65], v[82:85], v[214:217], v[50:65]
	ds_read_b64_tr_b16 v[214:215], v213 offset:0x200
	ds_read_b64_tr_b16 v[216:217], v213 offset:0xa00
	v_mfma_f32_32x32x16_bf16 v[50:65], v[86:89], v[218:221], v[50:65]
	ds_read_b64_tr_b16 v[218:219], v213 offset:0x1200
	ds_read_b64_tr_b16 v[220:221], v213 offset:0x1a00
	v_mfma_f32_32x32x16_bf16 v[50:65], v[90:93], v[222:225], v[50:65]
	ds_read_b64_tr_b16 v[222:223], v213 offset:0x2200
	ds_read_b64_tr_b16 v[224:225], v213 offset:0x2a00
	v_mfma_f32_32x32x16_bf16 v[50:65], v[94:97], v[226:229], v[50:65]
	ds_read_b64_tr_b16 v[226:227], v213 offset:0x3200
	ds_read_b64_tr_b16 v[228:229], v213 offset:0x3a00
	s_waitcnt lgkmcnt(0)
	v_mfma_f32_32x32x16_bf16 v[34:49], v[82:85], v[214:217], v[34:49]
	ds_read_b64_tr_b16 v[214:215], v213 offset:0x400
	ds_read_b64_tr_b16 v[216:217], v213 offset:0xc00
	v_mfma_f32_32x32x16_bf16 v[34:49], v[86:89], v[218:221], v[34:49]
	ds_read_b64_tr_b16 v[218:219], v213 offset:0x1400
	ds_read_b64_tr_b16 v[220:221], v213 offset:0x1c00
	v_mfma_f32_32x32x16_bf16 v[34:49], v[90:93], v[222:225], v[34:49]
	ds_read_b64_tr_b16 v[222:223], v213 offset:0x2400
	ds_read_b64_tr_b16 v[224:225], v213 offset:0x2c00
	v_mfma_f32_32x32x16_bf16 v[34:49], v[94:97], v[226:229], v[34:49]
	ds_read_b64_tr_b16 v[226:227], v213 offset:0x3400
	ds_read_b64_tr_b16 v[228:229], v213 offset:0x3c00
	s_waitcnt lgkmcnt(0)
	v_mfma_f32_32x32x16_bf16 v[18:33], v[82:85], v[214:217], v[18:33]
	ds_read_b64_tr_b16 v[214:215], v213 offset:0x600
	ds_read_b64_tr_b16 v[216:217], v213 offset:0xe00
	v_mfma_f32_32x32x16_bf16 v[18:33], v[86:89], v[218:221], v[18:33]
	ds_read_b64_tr_b16 v[218:219], v213 offset:0x1600
	ds_read_b64_tr_b16 v[220:221], v213 offset:0x1e00
	v_mfma_f32_32x32x16_bf16 v[18:33], v[90:93], v[222:225], v[18:33]
	ds_read_b64_tr_b16 v[222:223], v213 offset:0x2600
	ds_read_b64_tr_b16 v[224:225], v213 offset:0x2e00
	v_mfma_f32_32x32x16_bf16 v[18:33], v[94:97], v[226:229], v[18:33]
	ds_read_b64_tr_b16 v[226:227], v213 offset:0x3600
	ds_read_b64_tr_b16 v[228:229], v213 offset:0x3e00
	s_waitcnt lgkmcnt(0)
	v_mfma_f32_32x32x16_bf16 v[2:17], v[82:85], v[214:217], v[2:17]
	v_max_f32_e32 v82, v115, v115
	v_max_f32_e32 v83, v114, v114
	v_max_f32_e32 v82, v83, v82
	v_max3_f32 v83, v116, v117, v99
	v_max3_f32 v82, v82, v98, v100
	v_max3_f32 v82, v82, v101, v118
	v_max3_f32 v83, v83, v120, v121
	v_mfma_f32_32x32x16_bf16 v[2:17], v[86:89], v[218:221], v[2:17]
	v_max3_f32 v82, v82, v119, v102
	v_max3_f32 v83, v83, v104, v105
	v_max3_f32 v82, v82, v103, v122
	v_max3_f32 v83, v83, v124, v125
	v_max3_f32 v82, v82, v123, v106
	v_max3_f32 v83, v83, v108, v109
	v_max3_f32 v82, v82, v107, v126
	v_mfma_f32_32x32x16_bf16 v[2:17], v[90:93], v[222:225], v[2:17]
	v_max3_f32 v83, v83, v128, v129
	v_max3_f32 v82, v82, v127, v110
	v_max3_f32 v83, v83, v112, v113
	v_max3_f32 v82, v82, v111, v83
	v_mov_b32_e32 v83, v82
	s_nop 1
	v_permlane32_swap_b32_e32 v82, v83
	v_mfma_f32_32x32x16_bf16 v[2:17], v[94:97], v[226:229], v[2:17]
	v_max_f32_e32 v83, v83, v83
	v_max_f32_e32 v82, v82, v82
	v_max_f32_e32 v82, v82, v83
	v_cmp_lt_f32_e32 vcc, s40, v82
	s_cbranch_vccnz .LBB0_113
	v_mov_b32_e32 v213, 1.0
	v_cmp_gt_f32_e32 vcc, 1.0, v213
	s_cbranch_vccz .LBB0_106

; template <bool MLA>
; __device__ __forceinline__ void qkt(f32x16& p0, f32x16& p1, const char* Ks, const char* KRs, const bf16x8* qr, const char* qrl, const f32x16& negm, int r32, int hi) {
; #pragma unroll
;   for (int d0 = 0; d0 < 8; ++d0) { int cb = (d0 * 16 + hi * 8) * 2;
;     bf16x8 b0 = *reinterpret_cast<const bf16x8*>(Ks + KSWZ(r32, cb));
;     bf16x8 b1 = *reinterpret_cast<const bf16x8*>(Ks + KSWZ(32 + r32, cb));
;     if (d0 == 0) { p0 = __builtin_amdgcn_mfma_f32_32x32x16_bf16(b0, qr[0], negm, 0, 0, 0); p1 = __builtin_amdgcn_mfma_f32_32x32x16_bf16(b1, qr[0], negm, 0, 0, 0); }
;     else { p0 = __builtin_amdgcn_mfma_f32_32x32x16_bf16(b0, qr[d0], p0, 0, 0, 0); p1 = __builtin_amdgcn_mfma_f32_32x32x16_bf16(b1, qr[d0], p1, 0, 0, 0); } }
;   if constexpr (MLA) {
; #pragma unroll
;     for (int d0 = 0; d0 < 4; ++d0) { int ch = d0 * 2 + hi;
;       bf16x8 b0 = *reinterpret_cast<const bf16x8*>(KRs + KRSWZ(r32, ch));
;       bf16x8 b1 = *reinterpret_cast<const bf16x8*>(KRs + KRSWZ(32 + r32, ch));
;       const bf16x8 qq = *reinterpret_cast<const bf16x8*>(qrl + d0 * 1024);
;       p0 = __builtin_amdgcn_mfma_f32_32x32x16_bf16(b0, qq, p0, 0, 0, 0);
;       p1 = __builtin_amdgcn_mfma_f32_32x32x16_bf16(b1, qq, p1, 0, 0, 0); }
;   }
; }
.LBB0_106:
	s_waitcnt vmcnt(2)
	v_exp_f32_e32 v218, v114
	v_exp_f32_e32 v219, v115
	v_exp_f32_e32 v220, v116
	v_exp_f32_e32 v221, v117
	v_exp_f32_e32 v222, v118
	v_exp_f32_e32 v223, v119
	v_exp_f32_e32 v224, v120
	v_exp_f32_e32 v225, v121
	v_exp_f32_e32 v226, v122
	v_exp_f32_e32 v227, v123
	v_exp_f32_e32 v228, v124
	v_exp_f32_e32 v229, v125
	v_exp_f32_e32 v234, v126
	v_exp_f32_e32 v235, v127
	v_exp_f32_e32 v236, v128
	v_exp_f32_e32 v237, v129
	s_waitcnt vmcnt(2)
	s_barrier
	s_add_i32 s31, s19, s31
	v_add_u32_e32 v82, s27, v210
	ds_read_b128 v[176:179], v82 offset:57344
	ds_read_b128 v[82:85], v82 offset:49152
	v_add_u32_e32 v180, s27, v209
	s_add_i32 s2, s30, 0
	s_add_i32 s2, s2, 0x18000
	s_add_u32 vcc_lo, s28, s48
	s_addc_u32 vcc_hi, s29, s49
	s_add_i32 m0, s31, 0xc000
	v_lshl_add_u64 v[250:251], v[172:173], 0, vcc
	global_load_lds_dwordx4 v[250:251], off
	v_exp_f32_e32 v238, v100
	v_add_f32_e32 v255, 0, v218
	v_add_f32_e32 v255, v219, v255
	s_waitcnt lgkmcnt(0)
	v_mfma_f32_32x32x16_bf16 v[114:129], v[82:85], v[158:161], v[66:81]
	v_exp_f32_e32 v239, v101
	v_add_f32_e32 v255, v220, v255
	v_add_f32_e32 v255, v221, v255
	v_mfma_f32_32x32x16_bf16 v[82:97], v[176:179], v[158:161], v[66:81]
	ds_read_b128 v[176:179], v180 offset:57344
	ds_read_b128 v[180:183], v180 offset:49152
	s_add_u32 vcc_lo, s28, s48
	s_addc_u32 vcc_hi, s29, s49
	s_add_i32 m0, s31, 0xc400
	v_lshl_add_u64 v[250:251], v[174:175], 0, vcc
	global_load_lds_dwordx4 v[250:251], off
	v_exp_f32_e32 v246, v102
	v_add_f32_e32 v255, v222, v255
	v_add_f32_e32 v255, v223, v255
	s_waitcnt lgkmcnt(0)
	v_mfma_f32_32x32x16_bf16 v[114:129], v[180:183], v[154:157], v[114:129]
	v_exp_f32_e32 v247, v103
	v_add_f32_e32 v255, v224, v255
	v_add_f32_e32 v255, v225, v255
	v_add_u32_e32 v180, s27, v208
	v_mfma_f32_32x32x16_bf16 v[82:97], v[176:179], v[154:157], v[82:97]
	ds_read_b128 v[176:179], v180 offset:57344
	ds_read_b128 v[180:183], v180 offset:49152
	s_lshl_b32 s32, s24, 13
	s_add_u32 vcc_lo, s28, 0x2e360600
	s_addc_u32 vcc_hi, s29, 0
	s_add_i32 m0, s23, s32
	v_lshl_add_u64 v[250:251], v[168:169], 0, vcc
	global_load_lds_dwordx4 v[250:251], off
	v_exp_f32_e32 v249, v104
	v_add_f32_e32 v255, v226, v255
	v_add_f32_e32 v255, v227, v255
	s_waitcnt lgkmcnt(0)
	v_mfma_f32_32x32x16_bf16 v[114:129], v[180:183], v[150:153], v[114:129]
	v_exp_f32_e32 v252, v105
	v_add_f32_e32 v255, v228, v255
	v_add_f32_e32 v255, v229, v255
	v_add_u32_e32 v180, s27, v207
	v_mfma_f32_32x32x16_bf16 v[82:97], v[176:179], v[150:153], v[82:97]
	ds_read_b128 v[176:179], v180 offset:57344
	ds_read_b128 v[180:183], v180 offset:49152
	s_add_u32 vcc_lo, s28, 0x43c0100
	s_addc_u32 vcc_hi, s29, 0
	s_mov_b32 m0, s31
	v_lshl_add_u64 v[250:251], v[170:171], 0, vcc
	global_load_lds_dwordx4 v[250:251], off
	v_exp_f32_e32 v253, v106
	v_add_f32_e32 v255, v234, v255
	v_add_f32_e32 v255, v235, v255
	s_waitcnt lgkmcnt(0)
	v_mfma_f32_32x32x16_bf16 v[114:129], v[180:183], v[146:149], v[114:129]
	v_exp_f32_e32 v254, v107
	v_add_f32_e32 v255, v236, v255
	v_add_f32_e32 v255, v237, v255
	v_add_u32_e32 v180, s27, v206
	v_mfma_f32_32x32x16_bf16 v[82:97], v[176:179], v[146:149], v[82:97]
	ds_read_b128 v[176:179], v180 offset:57344
	ds_read_b128 v[180:183], v180 offset:49152
	s_add_u32 vcc_lo, s28, 0x43c0180
	s_addc_u32 vcc_hi, s29, 0
	s_add_i32 m0, s31, 0x400
	v_lshl_add_u64 v[250:251], v[170:171], 0, vcc
	global_load_lds_dwordx4 v[250:251], off
	v_cvt_pk_bf16_f32 v100, v218, v219
	v_exp_f32_e32 v98, v98
	s_waitcnt lgkmcnt(0)
	v_mfma_f32_32x32x16_bf16 v[114:129], v[180:183], v[142:145], v[114:129]
	v_cvt_pk_bf16_f32 v101, v220, v221
	v_exp_f32_e32 v99, v99
	v_add_u32_e32 v180, s27, v205
	v_mfma_f32_32x32x16_bf16 v[82:97], v[176:179], v[142:145], v[82:97]
	ds_read_b128 v[176:179], v180 offset:57344
	ds_read_b128 v[180:183], v180 offset:49152
	v_cvt_pk_bf16_f32 v102, v222, v223
	v_exp_f32_e32 v108, v108
	s_waitcnt lgkmcnt(0)
	v_mfma_f32_32x32x16_bf16 v[114:129], v[180:183], v[138:141], v[114:129]
	v_cvt_pk_bf16_f32 v103, v224, v225
	v_exp_f32_e32 v109, v109
	v_add_u32_e32 v180, s27, v204
	v_mfma_f32_32x32x16_bf16 v[82:97], v[176:179], v[138:141], v[82:97]
	ds_read_b128 v[176:179], v180 offset:57344
	ds_read_b128 v[180:183], v180 offset:49152
	v_cvt_pk_bf16_f32 v104, v226, v227
	v_exp_f32_e32 v110, v110
	s_waitcnt lgkmcnt(0)
	v_mfma_f32_32x32x16_bf16 v[114:129], v[180:183], v[134:137], v[114:129]
	v_cvt_pk_bf16_f32 v105, v228, v229
	v_exp_f32_e32 v111, v111
	v_add_u32_e32 v180, s27, v203
	v_mfma_f32_32x32x16_bf16 v[82:97], v[176:179], v[134:137], v[82:97]
	ds_read_b128 v[176:179], v180 offset:57344
	ds_read_b128 v[180:183], v180 offset:49152
	v_cvt_pk_bf16_f32 v106, v234, v235
	v_exp_f32_e32 v112, v112
	s_waitcnt lgkmcnt(0)
	v_mfma_f32_32x32x16_bf16 v[114:129], v[180:183], v[130:133], v[114:129]
	v_cvt_pk_bf16_f32 v107, v236, v237
	v_exp_f32_e32 v113, v113
	v_add_u32_e32 v180, s2, v200
	v_mfma_f32_32x32x16_bf16 v[82:97], v[176:179], v[130:133], v[82:97]
	ds_read_b128 v[176:179], v180
	ds_read_b128 v[180:183], v180 offset:4096
	ds_read_b128 v[214:217], v198
	v_add_f32_e32 v255, v98, v255
	v_add_f32_e32 v255, v99, v255
	s_waitcnt lgkmcnt(0)
	v_mfma_f32_32x32x16_bf16 v[114:129], v[176:179], v[214:217], v[114:129]
	v_add_f32_e32 v255, v238, v255
	v_add_f32_e32 v255, v239, v255
	v_mfma_f32_32x32x16_bf16 v[82:97], v[180:183], v[214:217], v[82:97]
	v_add_u32_e32 v180, s2, v201
	ds_read_b128 v[176:179], v180
	ds_read_b128 v[180:183], v180 offset:4096
	ds_read_b128 v[214:217], v198 offset:1024
	v_add_f32_e32 v255, v246, v255
	v_add_f32_e32 v255, v247, v255
	s_waitcnt lgkmcnt(0)
; #define SBAR() __builtin_amdgcn_sched_barrier(0)
; __device__ __forceinline__ float max3f(float a, float b, float c) { return __builtin_fmaxf(__builtin_fmaxf(a, b), c); }
; template <bool FIRST, bool MLA>
; __device__ __forceinline__ void partialSM(f32x16& p0, f32x16& p1, f32x16& negm, float& m_reg, float& alpha) {
;   float a = max3f(p0[0], p0[1], p1[0]), b = max3f(p0[2], p0[3], p1[1]); a = max3f(a, p1[2], p1[3]);
; #pragma unroll
;   for (int r = 4; r < 16; r += 4) { a = max3f(a, p0[r], p0[r + 1]); b = max3f(b, p0[r + 2], p0[r + 3]); a = max3f(a, p1[r], p1[r + 1]); b = max3f(b, p1[r + 2], p1[r + 3]); }
;   float pmax = fmaxf(a, b);
;   { auto rr = __builtin_amdgcn_permlane32_swap(__float_as_uint(pmax), __float_as_uint(pmax), false, false);
;     pmax = fmaxf(__uint_as_float(rr[0]), __uint_as_float(rr[1])); }
; template <int D0> __device__ __forceinline__ void pv_one(f32x16& od, int vb, bf16x8 pa0, bf16x8 pa1, bf16x8 pa2, bf16x8 pa3) {
;   const s16x4 l0 = tr_read<v_rd_off(D0, 0, 0)>(vb), h0 = tr_read<v_rd_off(D0, 0, 1)>(vb), l1 = tr_read<v_rd_off(D0, 1, 0)>(vb), h1 = tr_read<v_rd_off(D0, 1, 1)>(vb);
;   const s16x4 l2 = tr_read<v_rd_off(D0, 2, 0)>(vb), h2 = tr_read<v_rd_off(D0, 2, 1)>(vb), l3 = tr_read<v_rd_off(D0, 3, 0)>(vb), h3 = tr_read<v_rd_off(D0, 3, 1)>(vb);
;   asm volatile("s_waitcnt lgkmcnt(0)" ::: "memory"); SBAR();
;     ...
;   od = __builtin_amdgcn_mfma_f32_32x32x16_bf16(pa0, PK(l0, h0), od, 0, 0, 0);
;   od = __builtin_amdgcn_mfma_f32_32x32x16_bf16(pa1, PK(l1, h1), od, 0, 0, 0);
;   od = __builtin_amdgcn_mfma_f32_32x32x16_bf16(pa2, PK(l2, h2), od, 0, 0, 0);
;   od = __builtin_amdgcn_mfma_f32_32x32x16_bf16(pa3, PK(l3, h3), od, 0, 0, 0);
;     ...
; }
; __device__ __forceinline__ void pv_d0(f32x16* o, int vb, bf16x8 pa0, bf16x8 pa1, bf16x8 pa2, bf16x8 pa3) {
;   pv_one<0>(o[0], vb, pa0, pa1, pa2, pa3); pv_one<1>(o[1], vb, pa0, pa1, pa2, pa3); pv_one<2>(o[2], vb, pa0, pa1, pa2, pa3); pv_one<3>(o[3], vb, pa0, pa1, pa2, pa3);
; }
	v_mfma_f32_32x32x16_bf16 v[114:129], v[176:179], v[214:217], v[114:129]
	v_add_f32_e32 v255, v249, v255
	v_add_f32_e32 v255, v252, v255
	v_mfma_f32_32x32x16_bf16 v[82:97], v[180:183], v[214:217], v[82:97]
	v_add_u32_e32 v180, s2, v199
	ds_read_b128 v[176:179], v180
	ds_read_b128 v[180:183], v180 offset:4096
	ds_read_b128 v[214:217], v198 offset:2048
	v_add_f32_e32 v255, v253, v255
	v_add_f32_e32 v255, v254, v255
	s_waitcnt lgkmcnt(0)
	v_mfma_f32_32x32x16_bf16 v[114:129], v[176:179], v[214:217], v[114:129]
	v_add_f32_e32 v255, v108, v255
	v_add_f32_e32 v255, v109, v255
	v_mfma_f32_32x32x16_bf16 v[82:97], v[180:183], v[214:217], v[82:97]
	v_add_u32_e32 v180, s2, v202
	ds_read_b128 v[176:179], v180
	ds_read_b128 v[180:183], v180 offset:4096
	ds_read_b128 v[214:217], v198 offset:3072
	v_add_f32_e32 v255, v110, v255
	v_add_f32_e32 v255, v111, v255
	s_waitcnt lgkmcnt(0)
	v_mfma_f32_32x32x16_bf16 v[114:129], v[176:179], v[214:217], v[114:129]
	v_add_f32_e32 v255, v112, v255
	v_add_f32_e32 v255, v113, v255
	v_mfma_f32_32x32x16_bf16 v[82:97], v[180:183], v[214:217], v[82:97]
	v_cvt_pk_bf16_f32 v176, v253, v254
	v_cvt_pk_bf16_f32 v177, v108, v109
	v_cvt_pk_bf16_f32 v178, v110, v111
	v_cvt_pk_bf16_f32 v179, v112, v113
	v_cvt_pk_bf16_f32 v108, v98, v99
	v_cvt_pk_bf16_f32 v109, v238, v239
	v_cvt_pk_bf16_f32 v110, v246, v247
	v_cvt_pk_bf16_f32 v111, v249, v252
	v_mov_b32_e32 v98, v255
	v_add_u32_e32 v112, s11, v197
	ds_read_b64_tr_b16 v[180:181], v112 offset:0
	ds_read_b64_tr_b16 v[182:183], v112 offset:0x800
	ds_read_b64_tr_b16 v[214:215], v112 offset:0x1000
	ds_read_b64_tr_b16 v[216:217], v112 offset:0x1800
	ds_read_b64_tr_b16 v[218:219], v112 offset:0x2000
	ds_read_b64_tr_b16 v[220:221], v112 offset:0x2800
	ds_read_b64_tr_b16 v[222:223], v112 offset:0x3000
	ds_read_b64_tr_b16 v[224:225], v112 offset:0x3800
	s_waitcnt lgkmcnt(0)
	v_mov_b32_e32 v99, v98
	s_nop 1
	v_permlane32_swap_b32_e32 v98, v99
	v_permlane32_swap_b32_e32 v100, v102
	v_permlane32_swap_b32_e32 v176, v178
	v_permlane32_swap_b32_e32 v101, v103
	v_permlane32_swap_b32_e32 v104, v106
	v_permlane32_swap_b32_e32 v105, v107
	v_permlane32_swap_b32_e32 v108, v110
	v_permlane32_swap_b32_e32 v109, v111
	v_permlane32_swap_b32_e32 v177, v179
	v_mfma_f32_32x32x16_bf16 v[50:65], v[100:103], v[180:183], v[50:65]
	ds_read_b64_tr_b16 v[180:181], v112 offset:0x200
	ds_read_b64_tr_b16 v[182:183], v112 offset:0xa00
	v_mfma_f32_32x32x16_bf16 v[50:65], v[104:107], v[214:217], v[50:65]
	ds_read_b64_tr_b16 v[214:215], v112 offset:0x1200
	ds_read_b64_tr_b16 v[216:217], v112 offset:0x1a00
	v_mfma_f32_32x32x16_bf16 v[50:65], v[108:111], v[218:221], v[50:65]
	ds_read_b64_tr_b16 v[218:219], v112 offset:0x2200
	ds_read_b64_tr_b16 v[220:221], v112 offset:0x2a00
	v_mfma_f32_32x32x16_bf16 v[50:65], v[176:179], v[222:225], v[50:65]
	ds_read_b64_tr_b16 v[222:223], v112 offset:0x3200
	ds_read_b64_tr_b16 v[224:225], v112 offset:0x3a00
	s_waitcnt lgkmcnt(0)
	v_mfma_f32_32x32x16_bf16 v[34:49], v[100:103], v[180:183], v[34:49]
	ds_read_b64_tr_b16 v[180:181], v112 offset:0x400
	ds_read_b64_tr_b16 v[182:183], v112 offset:0xc00
	v_mfma_f32_32x32x16_bf16 v[34:49], v[104:107], v[214:217], v[34:49]
	ds_read_b64_tr_b16 v[214:215], v112 offset:0x1400
	ds_read_b64_tr_b16 v[216:217], v112 offset:0x1c00
	v_mfma_f32_32x32x16_bf16 v[34:49], v[108:111], v[218:221], v[34:49]
	ds_read_b64_tr_b16 v[218:219], v112 offset:0x2400
	ds_read_b64_tr_b16 v[220:221], v112 offset:0x2c00
	v_mfma_f32_32x32x16_bf16 v[34:49], v[176:179], v[222:225], v[34:49]
	ds_read_b64_tr_b16 v[222:223], v112 offset:0x3400
	ds_read_b64_tr_b16 v[224:225], v112 offset:0x3c00
	s_waitcnt lgkmcnt(0)
	v_mfma_f32_32x32x16_bf16 v[18:33], v[100:103], v[180:183], v[18:33]
	ds_read_b64_tr_b16 v[180:181], v112 offset:0x600
	ds_read_b64_tr_b16 v[182:183], v112 offset:0xe00
	v_mfma_f32_32x32x16_bf16 v[18:33], v[104:107], v[214:217], v[18:33]
	ds_read_b64_tr_b16 v[214:215], v112 offset:0x1600
	ds_read_b64_tr_b16 v[216:217], v112 offset:0x1e00
	v_mfma_f32_32x32x16_bf16 v[18:33], v[108:111], v[218:221], v[18:33]
	ds_read_b64_tr_b16 v[218:219], v112 offset:0x2600
	ds_read_b64_tr_b16 v[220:221], v112 offset:0x2e00
	v_mfma_f32_32x32x16_bf16 v[18:33], v[176:179], v[222:225], v[18:33]
	ds_read_b64_tr_b16 v[222:223], v112 offset:0x3600
	ds_read_b64_tr_b16 v[224:225], v112 offset:0x3e00
	s_waitcnt lgkmcnt(0)
	v_mfma_f32_32x32x16_bf16 v[2:17], v[100:103], v[180:183], v[2:17]
	v_max_f32_e32 v100, v115, v115
	v_max_f32_e32 v101, v114, v114
	v_max_f32_e32 v100, v101, v100
	v_max3_f32 v101, v116, v117, v83
	v_max3_f32 v100, v100, v82, v84
	v_max3_f32 v100, v100, v85, v118
	v_max3_f32 v101, v101, v120, v121
	v_mfma_f32_32x32x16_bf16 v[2:17], v[104:107], v[214:217], v[2:17]
	v_max3_f32 v100, v100, v119, v86
	v_max3_f32 v101, v101, v88, v89
	v_max3_f32 v100, v100, v87, v122
	v_max3_f32 v101, v101, v124, v125
	v_max3_f32 v100, v100, v123, v90
	v_max3_f32 v101, v101, v92, v93
	v_max3_f32 v100, v100, v91, v126
	v_mfma_f32_32x32x16_bf16 v[2:17], v[108:111], v[218:221], v[2:17]
	v_max3_f32 v101, v101, v128, v129
	v_max3_f32 v100, v100, v127, v94
	v_max3_f32 v101, v101, v96, v97
	v_max3_f32 v100, v100, v95, v101
	v_mov_b32_e32 v101, v100
	s_nop 1
	v_permlane32_swap_b32_e32 v100, v101
	v_mfma_f32_32x32x16_bf16 v[2:17], v[176:179], v[222:225], v[2:17]
	v_max_f32_e32 v101, v101, v101
	v_max_f32_e32 v100, v100, v100
	v_max_f32_e32 v100, v100, v101
	v_cmp_lt_f32_e32 vcc, s40, v100
	v_mov_b32_e32 v176, 1.0
	s_cbranch_vccnz .LBB0_114
	v_cmp_gt_f32_e32 vcc, 1.0, v176
	s_cbranch_vccz .LBB0_111

; #define SBAR() __builtin_amdgcn_sched_barrier(0)
; #define WAIT_BAR() do { asm volatile("s_waitcnt vmcnt(0)" ::: "memory"); __syncthreads(); } while (0)
; #define RESC(a) do { if (__any((a) < 1.f)) { if (hi == 0) al_l[r32] = (a); asm volatile("s_waitcnt lgkmcnt(0)" ::: "memory"); \
;     _Pragma("unroll") for (int d = 0; d < 4; ++d) _Pragma("unroll") for (int r = 0; r < 16; ++r) o[d][r] *= al_l[crow(r, hi)]; } } while (0)
; #define ROT() do { const int t_ = s_prev; s_prev = s_cur; s_cur = s_next; s_next = t_; } while (0)
; template <bool MLA> ...
;     ...
;   for (int j = 1; j + 1 < NT; j += 2) {
;     SBAR(); DMA_TILE(j + 1, s_next); SBAR();
;     qkt<MLA>(pB0, pB1, K_lds + s_cur * SHM_K, KR_lds + s_cur * SHM_KR, qr, qrl, negm, r32, hi);
;     finishSM(pA0, pA1, alA, l_reg, pa0, pa1, pa2, pa3);
;     pv_d0(o, vb0 + s_prev * SHM_V, pa0, pa1, pa2, pa3); partialSM<false, false>(pB0, pB1, negm, m_reg, alB);
;     RESC(alB); WAIT_BAR(); ROT();
;     SBAR(); DMA_TILE(j + 2, s_next); SBAR();
;     qkt<MLA>(pA0, pA1, K_lds + s_cur * SHM_K, KR_lds + s_cur * SHM_KR, qr, qrl, negm, r32, hi);
;     finishSM(pB0, pB1, alB, l_reg, pa0, pa1, pa2, pa3);
;     pv_d0(o, vb0 + s_prev * SHM_V, pa0, pa1, pa2, pa3); partialSM<false, false>(pA0, pA1, negm, m_reg, alA);
;     RESC(alA); WAIT_BAR(); ROT();
;   }
.LBB0_111:
	v_exp_f32_e32 v227, v114
	v_exp_f32_e32 v229, v115
	v_exp_f32_e32 v225, v116
	v_exp_f32_e32 v228, v117
	v_exp_f32_e32 v224, v118
	v_exp_f32_e32 v226, v119
	v_exp_f32_e32 v222, v120
	v_exp_f32_e32 v223, v121
	v_exp_f32_e32 v219, v122
	v_exp_f32_e32 v221, v123
	v_exp_f32_e32 v218, v124
	v_exp_f32_e32 v220, v125
	v_exp_f32_e32 v215, v126
	v_exp_f32_e32 v217, v127
	v_exp_f32_e32 v214, v128
	v_exp_f32_e32 v216, v129
	v_add_f32_e32 v0, v0, v212
	s_waitcnt vmcnt(2)
	v_fmac_f32_e32 v0, v211, v195
	v_add_f32_e32 v195, v98, v99
	s_add_i32 s26, s26, 2
	s_mov_b64 s[2:3], 0x40000
	v_fmac_f32_e32 v195, v0, v213
	v_lshl_add_u64 v[168:169], v[168:169], 0, s[2:3]
	v_lshl_add_u64 v[170:171], v[170:171], 0, s[50:51]
	v_lshl_add_u64 v[172:173], v[172:173], 0, s[50:51]
	s_cmpk_gt_u32 s26, 0x7c
	v_lshl_add_u64 v[174:175], v[174:175], 0, s[50:51]
	s_waitcnt vmcnt(2)
	s_barrier
	s_cbranch_scc1 .LBB0_116
	s_mov_b32 s35, s25
	s_mov_b32 s25, s10
	v_mov_b32_e32 v211, v176
	s_branch .LBB0_101

; #define SBAR() __builtin_amdgcn_sched_barrier(0)
; template <bool MLA>
; __device__ __forceinline__ void qkt(f32x16& p0, f32x16& p1, const char* Ks, const char* KRs, const bf16x8* qr, const char* qrl, const f32x16& negm, int r32, int hi) {
; #pragma unroll
;   for (int d0 = 0; d0 < 8; ++d0) { int cb = (d0 * 16 + hi * 8) * 2;
;     bf16x8 b0 = *reinterpret_cast<const bf16x8*>(Ks + KSWZ(r32, cb));
;     bf16x8 b1 = *reinterpret_cast<const bf16x8*>(Ks + KSWZ(32 + r32, cb));
;     if (d0 == 0) { p0 = __builtin_amdgcn_mfma_f32_32x32x16_bf16(b0, qr[0], negm, 0, 0, 0); p1 = __builtin_amdgcn_mfma_f32_32x32x16_bf16(b1, qr[0], negm, 0, 0, 0); }
;     else { p0 = __builtin_amdgcn_mfma_f32_32x32x16_bf16(b0, qr[d0], p0, 0, 0, 0); p1 = __builtin_amdgcn_mfma_f32_32x32x16_bf16(b1, qr[d0], p1, 0, 0, 0); } }
;   if constexpr (MLA) {
; #pragma unroll
;     for (int d0 = 0; d0 < 4; ++d0) { int ch = d0 * 2 + hi;
;       bf16x8 b0 = *reinterpret_cast<const bf16x8*>(KRs + KRSWZ(r32, ch));
;       bf16x8 b1 = *reinterpret_cast<const bf16x8*>(KRs + KRSWZ(32 + r32, ch));
;       const bf16x8 qq = *reinterpret_cast<const bf16x8*>(qrl + d0 * 1024);
;       p0 = __builtin_amdgcn_mfma_f32_32x32x16_bf16(b0, qq, p0, 0, 0, 0);
;       p1 = __builtin_amdgcn_mfma_f32_32x32x16_bf16(b1, qq, p1, 0, 0, 0); }
;   }
; }
; template <bool MLA> ...
;     ...
;   SBAR(); qkt<MLA>(pB0, pB1, K_lds + s_cur * SHM_K, KR_lds + s_cur * SHM_KR, qr, qrl, negm, r32, hi);
;   finishSM(pA0, pA1, alA, l_reg, pa0, pa1, pa2, pa3); SBAR();
.LBB0_116:
	s_waitcnt vmcnt(0)
	s_barrier
	s_add_i32 s2, 0, 0x10000
	v_add_u32_e32 v0, s2, v210
	ds_read_b128 v[168:171], v0 offset:8192
	ds_read_b128 v[98:101], v0
	v_add_u32_e32 v0, s2, v209
	v_exp_f32_e32 v83, v83
	v_exp_f32_e32 v96, v96
	v_exp_f32_e32 v97, v97
	s_waitcnt lgkmcnt(0)
	v_mfma_f32_32x32x16_bf16 v[114:129], v[98:101], v[158:161], v[66:81]
	v_mfma_f32_32x32x16_bf16 v[98:113], v[168:171], v[158:161], v[66:81]
	ds_read_b128 v[158:161], v0 offset:8192
	ds_read_b128 v[168:171], v0
	v_add_u32_e32 v0, s2, v208
	s_waitcnt lgkmcnt(0)
	v_mfma_f32_32x32x16_bf16 v[114:129], v[168:171], v[154:157], v[114:129]
	v_mfma_f32_32x32x16_bf16 v[98:113], v[158:161], v[154:157], v[98:113]
	ds_read_b128 v[154:157], v0 offset:8192
	ds_read_b128 v[158:161], v0
	v_add_u32_e32 v0, s2, v207
	s_waitcnt lgkmcnt(0)
	v_mfma_f32_32x32x16_bf16 v[114:129], v[158:161], v[150:153], v[114:129]
	v_mfma_f32_32x32x16_bf16 v[98:113], v[154:157], v[150:153], v[98:113]
	ds_read_b128 v[150:153], v0 offset:8192
	ds_read_b128 v[154:157], v0
	v_add_u32_e32 v0, s2, v206
	s_waitcnt lgkmcnt(0)
	v_mfma_f32_32x32x16_bf16 v[114:129], v[154:157], v[146:149], v[114:129]
	v_mfma_f32_32x32x16_bf16 v[98:113], v[150:153], v[146:149], v[98:113]
	ds_read_b128 v[146:149], v0 offset:8192
	ds_read_b128 v[150:153], v0
	v_add_u32_e32 v0, s2, v205
	s_waitcnt lgkmcnt(0)
	v_mfma_f32_32x32x16_bf16 v[114:129], v[150:153], v[142:145], v[114:129]
	v_mfma_f32_32x32x16_bf16 v[98:113], v[146:149], v[142:145], v[98:113]
	ds_read_b128 v[142:145], v0 offset:8192
	ds_read_b128 v[146:149], v0
	v_add_u32_e32 v0, s2, v204
	s_waitcnt lgkmcnt(0)
	v_mfma_f32_32x32x16_bf16 v[114:129], v[146:149], v[138:141], v[114:129]
	v_mfma_f32_32x32x16_bf16 v[98:113], v[142:145], v[138:141], v[98:113]
	ds_read_b128 v[138:141], v0 offset:8192
	ds_read_b128 v[142:145], v0
	v_add_u32_e32 v0, s2, v203
	s_add_i32 s2, 0, 0x1a000
	s_waitcnt lgkmcnt(0)
	v_mfma_f32_32x32x16_bf16 v[114:129], v[142:145], v[134:137], v[114:129]
	v_exp_f32_e32 v142, v95
	v_mfma_f32_32x32x16_bf16 v[98:113], v[138:141], v[134:137], v[98:113]
	ds_read_b128 v[134:137], v0 offset:8192
	ds_read_b128 v[138:141], v0
	v_add_u32_e32 v0, s2, v200
	s_waitcnt lgkmcnt(0)
	v_mfma_f32_32x32x16_bf16 v[114:129], v[138:141], v[130:133], v[114:129]
	v_mfma_f32_32x32x16_bf16 v[98:113], v[134:137], v[130:133], v[98:113]
	ds_read_b128 v[130:133], v0
	ds_read_b128 v[134:137], v0 offset:4096
	ds_read_b128 v[138:141], v198
	v_add_u32_e32 v0, s2, v201
	s_waitcnt lgkmcnt(0)
	v_mfma_f32_32x32x16_bf16 v[114:129], v[130:133], v[138:141], v[114:129]
	v_mfma_f32_32x32x16_bf16 v[98:113], v[134:137], v[138:141], v[98:113]
	ds_read_b128 v[130:133], v0
	ds_read_b128 v[134:137], v0 offset:4096
	ds_read_b128 v[138:141], v198 offset:1024
	v_add_u32_e32 v0, s2, v199
	s_waitcnt lgkmcnt(0)
	v_mfma_f32_32x32x16_bf16 v[114:129], v[130:133], v[138:141], v[114:129]
	v_mfma_f32_32x32x16_bf16 v[98:113], v[134:137], v[138:141], v[98:113]
	ds_read_b128 v[130:133], v0
	ds_read_b128 v[134:137], v0 offset:4096
	ds_read_b128 v[138:141], v198 offset:2048
	v_add_u32_e32 v0, s2, v202
	s_waitcnt lgkmcnt(0)
	v_mfma_f32_32x32x16_bf16 v[114:129], v[130:133], v[138:141], v[114:129]
	v_mfma_f32_32x32x16_bf16 v[98:113], v[134:137], v[138:141], v[98:113]
	ds_read_b128 v[130:133], v0
	ds_read_b128 v[134:137], v0 offset:4096
	ds_read_b128 v[138:141], v198 offset:3072
	v_add_f32_e32 v0, 0, v227
	v_add_f32_e32 v0, v229, v0
	v_add_f32_e32 v0, v225, v0
	v_add_f32_e32 v0, v228, v0
	v_add_f32_e32 v0, v224, v0
	v_add_f32_e32 v0, v226, v0
	v_add_f32_e32 v0, v222, v0
	v_add_f32_e32 v0, v223, v0
	v_add_f32_e32 v0, v219, v0
	v_add_f32_e32 v0, v221, v0
	v_add_f32_e32 v0, v218, v0
	v_add_f32_e32 v0, v220, v0
	s_waitcnt lgkmcnt(0)
; #define SBAR() __builtin_amdgcn_sched_barrier(0)
; __device__ __forceinline__ void finishSM(f32x16& p0, f32x16& p1, float alpha, float& l_reg, bf16x8& pa0, bf16x8& pa1, bf16x8& pa2, bf16x8& pa3) {
; #pragma unroll
;   for (int r = 0; r < 16; ++r) p1[r] = __builtin_amdgcn_exp2f(p1[r]);
;   float ps = 0;
; #pragma unroll
;   for (int r = 0; r < 16; ++r) ps += p0[r];
; #pragma unroll
;   for (int r = 0; r < 16; ++r) ps += p1[r];
;   { auto rr = __builtin_amdgcn_permlane32_swap(__float_as_uint(ps), __float_as_uint(ps), false, false);
;     ps = __uint_as_float(rr[0]) + __uint_as_float(rr[1]); }
;   l_reg = l_reg * alpha + ps;
;     ...
;   PK4(p0, 0, pa0); PK4(p0, 8, pa1); PK4(p1, 0, pa2); PK4(p1, 8, pa3);
;     ...
; }
; template <int D0> __device__ __forceinline__ void pv_one(f32x16& od, int vb, bf16x8 pa0, bf16x8 pa1, bf16x8 pa2, bf16x8 pa3) {
;   const s16x4 l0 = tr_read<v_rd_off(D0, 0, 0)>(vb), h0 = tr_read<v_rd_off(D0, 0, 1)>(vb), l1 = tr_read<v_rd_off(D0, 1, 0)>(vb), h1 = tr_read<v_rd_off(D0, 1, 1)>(vb);
;   const s16x4 l2 = tr_read<v_rd_off(D0, 2, 0)>(vb), h2 = tr_read<v_rd_off(D0, 2, 1)>(vb), l3 = tr_read<v_rd_off(D0, 3, 0)>(vb), h3 = tr_read<v_rd_off(D0, 3, 1)>(vb);
;   asm volatile("s_waitcnt lgkmcnt(0)" ::: "memory"); SBAR();
;     ...
;   od = __builtin_amdgcn_mfma_f32_32x32x16_bf16(pa0, PK(l0, h0), od, 0, 0, 0);
;   od = __builtin_amdgcn_mfma_f32_32x32x16_bf16(pa1, PK(l1, h1), od, 0, 0, 0);
;   od = __builtin_amdgcn_mfma_f32_32x32x16_bf16(pa2, PK(l2, h2), od, 0, 0, 0);
;   od = __builtin_amdgcn_mfma_f32_32x32x16_bf16(pa3, PK(l3, h3), od, 0, 0, 0);
;     ...
; }
	v_mfma_f32_32x32x16_bf16 v[114:129], v[130:133], v[138:141], v[114:129]
	v_exp_f32_e32 v130, v82
	v_add_f32_e32 v0, v215, v0
	v_add_f32_e32 v0, v217, v0
	v_exp_f32_e32 v131, v84
	v_add_f32_e32 v0, v214, v0
	v_exp_f32_e32 v132, v85
	v_add_f32_e32 v0, v216, v0
	v_exp_f32_e32 v133, v86
	v_add_f32_e32 v0, v130, v0
	v_mfma_f32_32x32x16_bf16 v[98:113], v[134:137], v[138:141], v[98:113]
	v_exp_f32_e32 v134, v87
	v_add_f32_e32 v0, v83, v0
	v_exp_f32_e32 v135, v88
	v_add_f32_e32 v0, v131, v0
	v_exp_f32_e32 v136, v89
	v_add_f32_e32 v0, v132, v0
	v_exp_f32_e32 v137, v90
	v_add_f32_e32 v0, v133, v0
	v_exp_f32_e32 v138, v91
	v_add_f32_e32 v0, v134, v0
	v_exp_f32_e32 v139, v92
	v_add_f32_e32 v0, v135, v0
	v_exp_f32_e32 v140, v93
	v_add_f32_e32 v0, v136, v0
	v_exp_f32_e32 v141, v94
	v_add_f32_e32 v0, v137, v0
	v_add_f32_e32 v0, v138, v0
	v_add_f32_e32 v0, v139, v0
	v_add_f32_e32 v0, v140, v0
	v_add_f32_e32 v0, v141, v0
	v_add_f32_e32 v0, v142, v0
	v_add_f32_e32 v0, v96, v0
	v_add_f32_e32 v0, v97, v0
	v_mov_b32_e32 v82, v0
	v_cvt_pk_bf16_f32 v84, v227, v229
	v_cvt_pk_bf16_f32 v85, v225, v228
	v_cvt_pk_bf16_f32 v86, v224, v226
	s_nop 1
	v_permlane32_swap_b32_e32 v0, v82
	v_cvt_pk_bf16_f32 v87, v222, v223
	v_permlane32_swap_b32_e32 v84, v86
	v_cvt_pk_bf16_f32 v88, v219, v221
	v_cvt_pk_bf16_f32 v89, v218, v220
	v_cvt_pk_bf16_f32 v90, v215, v217
	v_cvt_pk_bf16_f32 v91, v214, v216
	v_cvt_pk_bf16_f32 v92, v130, v83
	v_cvt_pk_bf16_f32 v93, v131, v132
	v_cvt_pk_bf16_f32 v94, v133, v134
	v_cvt_pk_bf16_f32 v95, v135, v136
	v_cvt_pk_bf16_f32 v130, v137, v138
	v_cvt_pk_bf16_f32 v131, v139, v140
	v_cvt_pk_bf16_f32 v132, v141, v142
	v_cvt_pk_bf16_f32 v133, v96, v97
	v_permlane32_swap_b32_e32 v85, v87
	v_permlane32_swap_b32_e32 v88, v90
	v_permlane32_swap_b32_e32 v89, v91
	v_permlane32_swap_b32_e32 v92, v94
	v_permlane32_swap_b32_e32 v93, v95
	v_permlane32_swap_b32_e32 v130, v132
	v_permlane32_swap_b32_e32 v131, v133
	ds_read_b64_tr_b16 v[134:135], v197 offset:0
	ds_read_b64_tr_b16 v[136:137], v197 offset:0x800
	ds_read_b64_tr_b16 v[138:139], v197 offset:0x1000
	ds_read_b64_tr_b16 v[140:141], v197 offset:0x1800
	ds_read_b64_tr_b16 v[142:143], v197 offset:0x2000
	ds_read_b64_tr_b16 v[144:145], v197 offset:0x2800
	ds_read_b64_tr_b16 v[146:147], v197 offset:0x3000
	ds_read_b64_tr_b16 v[148:149], v197 offset:0x3800
	s_waitcnt lgkmcnt(0)
	s_nop 0
	v_mfma_f32_32x32x16_bf16 v[50:65], v[84:87], v[134:137], v[50:65]
	ds_read_b64_tr_b16 v[134:135], v197 offset:0x200
	ds_read_b64_tr_b16 v[136:137], v197 offset:0xa00
	v_mfma_f32_32x32x16_bf16 v[50:65], v[88:91], v[138:141], v[50:65]
	ds_read_b64_tr_b16 v[138:139], v197 offset:0x1200
	ds_read_b64_tr_b16 v[140:141], v197 offset:0x1a00
	v_mfma_f32_32x32x16_bf16 v[50:65], v[92:95], v[142:145], v[50:65]
	ds_read_b64_tr_b16 v[142:143], v197 offset:0x2200
	ds_read_b64_tr_b16 v[144:145], v197 offset:0x2a00
	v_mfma_f32_32x32x16_bf16 v[50:65], v[130:133], v[146:149], v[50:65]
	ds_read_b64_tr_b16 v[146:147], v197 offset:0x3200
	ds_read_b64_tr_b16 v[148:149], v197 offset:0x3a00
	s_waitcnt lgkmcnt(0)
	v_mfma_f32_32x32x16_bf16 v[34:49], v[84:87], v[134:137], v[34:49]
	ds_read_b64_tr_b16 v[134:135], v197 offset:0x400
	ds_read_b64_tr_b16 v[136:137], v197 offset:0xc00
	v_mfma_f32_32x32x16_bf16 v[34:49], v[88:91], v[138:141], v[34:49]
	ds_read_b64_tr_b16 v[138:139], v197 offset:0x1400
	ds_read_b64_tr_b16 v[140:141], v197 offset:0x1c00
	v_mfma_f32_32x32x16_bf16 v[34:49], v[92:95], v[142:145], v[34:49]
	ds_read_b64_tr_b16 v[142:143], v197 offset:0x2400
	ds_read_b64_tr_b16 v[144:145], v197 offset:0x2c00
	v_mfma_f32_32x32x16_bf16 v[34:49], v[130:133], v[146:149], v[34:49]
	ds_read_b64_tr_b16 v[146:147], v197 offset:0x3400
	ds_read_b64_tr_b16 v[148:149], v197 offset:0x3c00
	s_waitcnt lgkmcnt(0)
	v_mfma_f32_32x32x16_bf16 v[18:33], v[84:87], v[134:137], v[18:33]
	ds_read_b64_tr_b16 v[134:135], v197 offset:0x600
	ds_read_b64_tr_b16 v[136:137], v197 offset:0xe00
	v_mfma_f32_32x32x16_bf16 v[18:33], v[88:91], v[138:141], v[18:33]
	ds_read_b64_tr_b16 v[138:139], v197 offset:0x1600
	ds_read_b64_tr_b16 v[140:141], v197 offset:0x1e00
	v_mfma_f32_32x32x16_bf16 v[18:33], v[92:95], v[142:145], v[18:33]
	ds_read_b64_tr_b16 v[142:143], v197 offset:0x2600
	ds_read_b64_tr_b16 v[144:145], v197 offset:0x2e00
	v_mfma_f32_32x32x16_bf16 v[18:33], v[130:133], v[146:149], v[18:33]
	ds_read_b64_tr_b16 v[146:147], v197 offset:0x3600
	ds_read_b64_tr_b16 v[148:149], v197 offset:0x3e00
	s_waitcnt lgkmcnt(0)
	v_mfma_f32_32x32x16_bf16 v[2:17], v[84:87], v[134:137], v[2:17]
	v_max_f32_e32 v83, v115, v115
	v_max_f32_e32 v84, v114, v114
	v_max_f32_e32 v83, v84, v83
	v_max3_f32 v84, v116, v117, v99
	v_max3_f32 v83, v83, v98, v100
	v_max3_f32 v83, v83, v101, v118
	v_max3_f32 v84, v84, v120, v121
	v_mfma_f32_32x32x16_bf16 v[2:17], v[88:91], v[138:141], v[2:17]
	v_max3_f32 v83, v83, v119, v102
	v_max3_f32 v84, v84, v104, v105
	v_max3_f32 v83, v83, v103, v122
	v_max3_f32 v84, v84, v124, v125
	v_max3_f32 v83, v83, v123, v106
	v_max3_f32 v84, v84, v108, v109
	v_max3_f32 v83, v83, v107, v126
	v_mfma_f32_32x32x16_bf16 v[2:17], v[92:95], v[142:145], v[2:17]
	v_max3_f32 v84, v84, v128, v129
	v_max3_f32 v83, v83, v127, v110
	v_max3_f32 v84, v84, v112, v113
	v_max3_f32 v83, v83, v111, v84
	v_mov_b32_e32 v84, v83
	s_nop 1
	v_permlane32_swap_b32_e32 v83, v84
	v_mfma_f32_32x32x16_bf16 v[2:17], v[130:133], v[146:149], v[2:17]
	v_max_f32_e32 v84, v84, v84
	v_max_f32_e32 v83, v83, v83
	v_max_f32_e32 v84, v83, v84
	v_cmp_lt_f32_e32 vcc, s40, v84
	v_mov_b32_e32 v83, 1.0
	s_cbranch_vccnz .LBB0_146
	v_cmp_gt_f32_e32 vcc, 1.0, v83
	s_cbranch_vccz .LBB0_121

; template <bool MLA>
; __device__ __forceinline__ void qkt(f32x16& p0, f32x16& p1, const char* Ks, const char* KRs, const bf16x8* qr, const char* qrl, const f32x16& negm, int r32, int hi) {
; #pragma unroll
;   for (int d0 = 0; d0 < 8; ++d0) { int cb = (d0 * 16 + hi * 8) * 2;
;     bf16x8 b0 = *reinterpret_cast<const bf16x8*>(Ks + KSWZ(r32, cb));
;     bf16x8 b1 = *reinterpret_cast<const bf16x8*>(Ks + KSWZ(32 + r32, cb));
;     if (d0 == 0) { p0 = __builtin_amdgcn_mfma_f32_32x32x16_bf16(b0, qr[0], negm, 0, 0, 0); p1 = __builtin_amdgcn_mfma_f32_32x32x16_bf16(b1, qr[0], negm, 0, 0, 0); }
;     else { p0 = __builtin_amdgcn_mfma_f32_32x32x16_bf16(b0, qr[d0], p0, 0, 0, 0); p1 = __builtin_amdgcn_mfma_f32_32x32x16_bf16(b1, qr[d0], p1, 0, 0, 0); } }
.LBB0_125:
	s_mov_b32 s13, s16
	s_mov_b32 s16, s23
	s_lshl_b32 s8, s17, 14
	s_add_i32 s23, s8, 0
	s_add_i32 s32, s23, s14
	s_lshl_b32 s19, s13, 14
	s_add_i32 s8, s19, 0
	v_add_u32_e32 v98, s8, v199
	ds_read_b128 v[220:223], v98 offset:57344
	ds_read_b128 v[98:101], v98 offset:49152
	v_add_u32_e32 v246, s8, v198
	ds_read_b128 v[238:241], v246 offset:57344
	ds_read_b128 v[242:245], v246 offset:49152
	v_add_u32_e32 v201, s8, v197
	s_add_u32 vcc_lo, s2, s62
	s_addc_u32 vcc_hi, s3, s63
	s_add_i32 m0, s32, 0xc000
	v_lshl_add_u64 v[250:251], v[168:169], 0, vcc
	global_load_lds_dwordx4 v[250:251], off
	v_exp_f32_e32 v203, v82
	v_add_f32_e32 v82, 0, v217
	v_add_f32_e32 v82, v219, v82
	s_waitcnt lgkmcnt(2)
	v_mfma_f32_32x32x16_bf16 v[114:129], v[98:101], v[158:161], v[66:81]
	v_add_f32_e32 v82, v215, v82
	v_add_f32_e32 v82, v218, v82
	v_add_f32_e32 v82, v214, v82
	v_add_f32_e32 v82, v216, v82
	v_add_f32_e32 v82, v212, v82
	v_add_f32_e32 v82, v213, v82
	v_add_f32_e32 v82, v209, v82
	v_mfma_f32_32x32x16_bf16 v[98:113], v[220:223], v[158:161], v[66:81]
	ds_read_b128 v[220:223], v201 offset:57344
	ds_read_b128 v[224:227], v201 offset:49152
	v_add_u32_e32 v201, s8, v196
	s_add_u32 vcc_lo, s2, s62
	s_addc_u32 vcc_hi, s3, s63
	s_add_i32 m0, s32, 0xc400
	v_lshl_add_u64 v[250:251], v[170:171], 0, vcc
	global_load_lds_dwordx4 v[250:251], off
	v_add_f32_e32 v82, v211, v82
	v_add_f32_e32 v82, v208, v82
	v_add_f32_e32 v82, v210, v82
	v_add_f32_e32 v82, v205, v82
	v_add_f32_e32 v82, v207, v82
	s_waitcnt lgkmcnt(2)
	v_mfma_f32_32x32x16_bf16 v[98:113], v[238:241], v[154:157], v[98:113]
	v_add_f32_e32 v82, v204, v82
	v_add_f32_e32 v82, v206, v82
	v_add_f32_e32 v82, v203, v82
	v_exp_f32_e32 v228, v91
	v_exp_f32_e32 v229, v92
	v_exp_f32_e32 v234, v93
	v_exp_f32_e32 v235, v94
	v_mfma_f32_32x32x16_bf16 v[114:129], v[242:245], v[154:157], v[114:129]
	ds_read_b128 v[238:241], v201 offset:57344
	ds_read_b128 v[242:245], v201 offset:49152
	v_add_u32_e32 v201, s8, v195
	s_add_u32 vcc_lo, s2, 0x1c3c1600
	s_addc_u32 vcc_hi, s3, 0
	s_mov_b32 m0, s32
	v_lshl_add_u64 v[250:251], v[0:1], 0, vcc
	global_load_lds_dwordx4 v[250:251], off
	v_exp_f32_e32 v236, v95
	v_exp_f32_e32 v237, v96
	v_exp_f32_e32 v97, v97
	s_lshl_b32 s24, s16, 14
	s_waitcnt lgkmcnt(2)
	v_mfma_f32_32x32x16_bf16 v[98:113], v[220:223], v[150:153], v[98:113]
	v_mfma_f32_32x32x16_bf16 v[114:129], v[224:227], v[150:153], v[114:129]
	ds_read_b128 v[220:223], v201 offset:57344
	ds_read_b128 v[224:227], v201 offset:49152
	v_add_u32_e32 v201, s8, v183
	s_add_u32 vcc_lo, s2, 0x1c3c1680
	s_addc_u32 vcc_hi, s3, 0
	s_add_i32 m0, s32, 0x400
	v_lshl_add_u64 v[250:251], v[0:1], 0, vcc
	global_load_lds_dwordx4 v[250:251], off
	s_waitcnt lgkmcnt(2)
	v_mfma_f32_32x32x16_bf16 v[98:113], v[238:241], v[146:149], v[98:113]
	v_mfma_f32_32x32x16_bf16 v[114:129], v[242:245], v[146:149], v[114:129]
	ds_read_b128 v[238:241], v201 offset:57344
	ds_read_b128 v[242:245], v201 offset:49152
	v_add_u32_e32 v201, s8, v193
	s_waitcnt lgkmcnt(2)
	v_mfma_f32_32x32x16_bf16 v[98:113], v[220:223], v[142:145], v[98:113]
	v_mfma_f32_32x32x16_bf16 v[114:129], v[224:227], v[142:145], v[114:129]
	ds_read_b128 v[220:223], v201 offset:57344
	ds_read_b128 v[224:227], v201 offset:49152
	v_add_u32_e32 v201, s8, v194
	s_waitcnt lgkmcnt(2)
	v_mfma_f32_32x32x16_bf16 v[98:113], v[238:241], v[138:141], v[98:113]
	v_mfma_f32_32x32x16_bf16 v[114:129], v[242:245], v[138:141], v[114:129]
	ds_read_b128 v[238:241], v201 offset:57344
	ds_read_b128 v[242:245], v201 offset:49152
	s_waitcnt lgkmcnt(2)
	v_mfma_f32_32x32x16_bf16 v[98:113], v[220:223], v[134:137], v[98:113]
	v_mfma_f32_32x32x16_bf16 v[114:129], v[224:227], v[134:137], v[114:129]
	s_waitcnt lgkmcnt(0)
; #define SBAR() __builtin_amdgcn_sched_barrier(0)
; __device__ __forceinline__ void finishSM(f32x16& p0, f32x16& p1, float alpha, float& l_reg, bf16x8& pa0, bf16x8& pa1, bf16x8& pa2, bf16x8& pa3) {
; #pragma unroll
;   for (int r = 0; r < 16; ++r) p1[r] = __builtin_amdgcn_exp2f(p1[r]);
;   float ps = 0;
; #pragma unroll
;   for (int r = 0; r < 16; ++r) ps += p0[r];
; #pragma unroll
;   for (int r = 0; r < 16; ++r) ps += p1[r];
;   { auto rr = __builtin_amdgcn_permlane32_swap(__float_as_uint(ps), __float_as_uint(ps), false, false);
;     ps = __uint_as_float(rr[0]) + __uint_as_float(rr[1]); }
;   l_reg = l_reg * alpha + ps;
;     ...
;   PK4(p0, 0, pa0); PK4(p0, 8, pa1); PK4(p1, 0, pa2); PK4(p1, 8, pa3);
;     ...
; }
; template <int D0> __device__ __forceinline__ void pv_one(f32x16& od, int vb, bf16x8 pa0, bf16x8 pa1, bf16x8 pa2, bf16x8 pa3) {
;   const s16x4 l0 = tr_read<v_rd_off(D0, 0, 0)>(vb), h0 = tr_read<v_rd_off(D0, 0, 1)>(vb), l1 = tr_read<v_rd_off(D0, 1, 0)>(vb), h1 = tr_read<v_rd_off(D0, 1, 1)>(vb);
;   const s16x4 l2 = tr_read<v_rd_off(D0, 2, 0)>(vb), h2 = tr_read<v_rd_off(D0, 2, 1)>(vb), l3 = tr_read<v_rd_off(D0, 3, 0)>(vb), h3 = tr_read<v_rd_off(D0, 3, 1)>(vb);
;   asm volatile("s_waitcnt lgkmcnt(0)" ::: "memory"); SBAR();
;     ...
;   od = __builtin_amdgcn_mfma_f32_32x32x16_bf16(pa0, PK(l0, h0), od, 0, 0, 0);
;   od = __builtin_amdgcn_mfma_f32_32x32x16_bf16(pa1, PK(l1, h1), od, 0, 0, 0);
;   od = __builtin_amdgcn_mfma_f32_32x32x16_bf16(pa2, PK(l2, h2), od, 0, 0, 0);
;   od = __builtin_amdgcn_mfma_f32_32x32x16_bf16(pa3, PK(l3, h3), od, 0, 0, 0);
;     ...
; }
	v_mfma_f32_32x32x16_bf16 v[98:113], v[238:241], v[130:133], v[98:113]
	v_exp_f32_e32 v220, v83
	v_exp_f32_e32 v221, v84
	v_exp_f32_e32 v222, v85
	v_exp_f32_e32 v223, v86
	v_add_f32_e32 v82, v220, v82
	v_add_f32_e32 v82, v221, v82
	v_add_f32_e32 v82, v222, v82
	v_mfma_f32_32x32x16_bf16 v[114:129], v[242:245], v[130:133], v[114:129]
	v_exp_f32_e32 v224, v87
	v_exp_f32_e32 v225, v88
	v_exp_f32_e32 v226, v89
	v_exp_f32_e32 v227, v90
	v_add_f32_e32 v82, v223, v82
	v_add_f32_e32 v82, v224, v82
	v_add_f32_e32 v82, v225, v82
	v_add_f32_e32 v82, v226, v82
	v_add_f32_e32 v82, v227, v82
	v_add_f32_e32 v82, v228, v82
	v_add_f32_e32 v82, v229, v82
	v_add_f32_e32 v82, v234, v82
	v_add_f32_e32 v82, v235, v82
	v_add_f32_e32 v82, v236, v82
	v_add_f32_e32 v82, v237, v82
	v_add_f32_e32 v201, v97, v82
	v_cvt_pk_bf16_f32 v82, v217, v219
	v_cvt_pk_bf16_f32 v83, v215, v218
	v_cvt_pk_bf16_f32 v84, v214, v216
	v_cvt_pk_bf16_f32 v85, v212, v213
	v_cvt_pk_bf16_f32 v86, v209, v211
	v_cvt_pk_bf16_f32 v87, v208, v210
	v_cvt_pk_bf16_f32 v88, v205, v207
	v_cvt_pk_bf16_f32 v89, v204, v206
	v_cvt_pk_bf16_f32 v90, v203, v220
	v_cvt_pk_bf16_f32 v91, v221, v222
	v_cvt_pk_bf16_f32 v92, v223, v224
	v_cvt_pk_bf16_f32 v93, v225, v226
	v_cvt_pk_bf16_f32 v94, v227, v228
	v_cvt_pk_bf16_f32 v95, v229, v234
	v_cvt_pk_bf16_f32 v96, v235, v236
	v_cvt_pk_bf16_f32 v97, v237, v97
	v_add_u32_e32 v203, s24, v182
	ds_read_b64_tr_b16 v[204:205], v203 offset:0
	ds_read_b64_tr_b16 v[206:207], v203 offset:0x800
	ds_read_b64_tr_b16 v[208:209], v203 offset:0x1000
	ds_read_b64_tr_b16 v[210:211], v203 offset:0x1800
	ds_read_b64_tr_b16 v[212:213], v203 offset:0x2000
	ds_read_b64_tr_b16 v[214:215], v203 offset:0x2800
	ds_read_b64_tr_b16 v[216:217], v203 offset:0x3000
	ds_read_b64_tr_b16 v[218:219], v203 offset:0x3800
	s_waitcnt lgkmcnt(0)
	v_mov_b32_e32 v202, v201
	s_nop 1
	v_permlane32_swap_b32_e32 v201, v202
	v_permlane32_swap_b32_e32 v82, v84
	v_permlane32_swap_b32_e32 v83, v85
	v_permlane32_swap_b32_e32 v86, v88
	v_permlane32_swap_b32_e32 v87, v89
	v_permlane32_swap_b32_e32 v90, v92
	v_permlane32_swap_b32_e32 v91, v93
	v_permlane32_swap_b32_e32 v94, v96
	v_permlane32_swap_b32_e32 v95, v97
	v_mfma_f32_32x32x16_bf16 v[2:17], v[82:85], v[204:207], v[2:17]
	ds_read_b64_tr_b16 v[204:205], v203 offset:0x200
	ds_read_b64_tr_b16 v[206:207], v203 offset:0xa00
	v_mfma_f32_32x32x16_bf16 v[2:17], v[86:89], v[208:211], v[2:17]
	ds_read_b64_tr_b16 v[208:209], v203 offset:0x1200
	ds_read_b64_tr_b16 v[210:211], v203 offset:0x1a00
	v_mfma_f32_32x32x16_bf16 v[2:17], v[90:93], v[212:215], v[2:17]
	ds_read_b64_tr_b16 v[212:213], v203 offset:0x2200
	ds_read_b64_tr_b16 v[214:215], v203 offset:0x2a00
	v_mfma_f32_32x32x16_bf16 v[2:17], v[94:97], v[216:219], v[2:17]
	ds_read_b64_tr_b16 v[216:217], v203 offset:0x3200
	ds_read_b64_tr_b16 v[218:219], v203 offset:0x3a00
	s_waitcnt lgkmcnt(0)
	v_mfma_f32_32x32x16_bf16 v[50:65], v[82:85], v[204:207], v[50:65]
	ds_read_b64_tr_b16 v[204:205], v203 offset:0x400
	ds_read_b64_tr_b16 v[206:207], v203 offset:0xc00
	v_mfma_f32_32x32x16_bf16 v[50:65], v[86:89], v[208:211], v[50:65]
	ds_read_b64_tr_b16 v[208:209], v203 offset:0x1400
	ds_read_b64_tr_b16 v[210:211], v203 offset:0x1c00
	v_mfma_f32_32x32x16_bf16 v[50:65], v[90:93], v[212:215], v[50:65]
	ds_read_b64_tr_b16 v[212:213], v203 offset:0x2400
	ds_read_b64_tr_b16 v[214:215], v203 offset:0x2c00
	v_mfma_f32_32x32x16_bf16 v[50:65], v[94:97], v[216:219], v[50:65]
	ds_read_b64_tr_b16 v[216:217], v203 offset:0x3400
	ds_read_b64_tr_b16 v[218:219], v203 offset:0x3c00
	s_waitcnt lgkmcnt(0)
	v_mfma_f32_32x32x16_bf16 v[34:49], v[82:85], v[204:207], v[34:49]
	ds_read_b64_tr_b16 v[204:205], v203 offset:0x600
	ds_read_b64_tr_b16 v[206:207], v203 offset:0xe00
	v_mfma_f32_32x32x16_bf16 v[34:49], v[86:89], v[208:211], v[34:49]
	ds_read_b64_tr_b16 v[208:209], v203 offset:0x1600
	ds_read_b64_tr_b16 v[210:211], v203 offset:0x1e00
	v_mfma_f32_32x32x16_bf16 v[34:49], v[90:93], v[212:215], v[34:49]
	ds_read_b64_tr_b16 v[212:213], v203 offset:0x2600
	ds_read_b64_tr_b16 v[214:215], v203 offset:0x2e00
	v_mfma_f32_32x32x16_bf16 v[34:49], v[94:97], v[216:219], v[34:49]
	ds_read_b64_tr_b16 v[216:217], v203 offset:0x3600
	ds_read_b64_tr_b16 v[218:219], v203 offset:0x3e00
	s_waitcnt lgkmcnt(0)
	v_mfma_f32_32x32x16_bf16 v[18:33], v[82:85], v[204:207], v[18:33]
	v_max_f32_e32 v82, v115, v115
	v_max_f32_e32 v83, v114, v114
	v_max_f32_e32 v82, v83, v82
	v_max3_f32 v83, v116, v117, v99
	v_max3_f32 v82, v82, v98, v100
	v_max3_f32 v82, v82, v101, v118
	v_max3_f32 v83, v83, v120, v121
	v_mfma_f32_32x32x16_bf16 v[18:33], v[86:89], v[208:211], v[18:33]
	v_max3_f32 v82, v82, v119, v102
	v_max3_f32 v83, v83, v104, v105
	v_max3_f32 v82, v82, v103, v122
	v_max3_f32 v83, v83, v124, v125
	v_max3_f32 v82, v82, v123, v106
	v_max3_f32 v83, v83, v108, v109
	v_max3_f32 v82, v82, v107, v126
	v_mfma_f32_32x32x16_bf16 v[18:33], v[90:93], v[212:215], v[18:33]
	v_max3_f32 v83, v83, v128, v129
	v_max3_f32 v82, v82, v127, v110
	v_max3_f32 v83, v83, v112, v113
	v_max3_f32 v82, v82, v111, v83
	v_mov_b32_e32 v83, v82
	s_nop 1
	v_permlane32_swap_b32_e32 v82, v83
	v_mfma_f32_32x32x16_bf16 v[18:33], v[94:97], v[216:219], v[18:33]
	v_max_f32_e32 v83, v83, v83
	v_max_f32_e32 v82, v82, v82
	v_max_f32_e32 v82, v82, v83
	v_cmp_lt_f32_e32 vcc, s40, v82
	s_cbranch_vccnz .LBB0_137
	v_mov_b32_e32 v203, 1.0
	v_cmp_gt_f32_e32 vcc, 1.0, v203
	s_cbranch_vccz .LBB0_130

; template <bool MLA>
; __device__ __forceinline__ void qkt(f32x16& p0, f32x16& p1, const char* Ks, const char* KRs, const bf16x8* qr, const char* qrl, const f32x16& negm, int r32, int hi) {
; #pragma unroll
;   for (int d0 = 0; d0 < 8; ++d0) { int cb = (d0 * 16 + hi * 8) * 2;
;     bf16x8 b0 = *reinterpret_cast<const bf16x8*>(Ks + KSWZ(r32, cb));
;     bf16x8 b1 = *reinterpret_cast<const bf16x8*>(Ks + KSWZ(32 + r32, cb));
;     if (d0 == 0) { p0 = __builtin_amdgcn_mfma_f32_32x32x16_bf16(b0, qr[0], negm, 0, 0, 0); p1 = __builtin_amdgcn_mfma_f32_32x32x16_bf16(b1, qr[0], negm, 0, 0, 0); }
;     else { p0 = __builtin_amdgcn_mfma_f32_32x32x16_bf16(b0, qr[d0], p0, 0, 0, 0); p1 = __builtin_amdgcn_mfma_f32_32x32x16_bf16(b1, qr[d0], p1, 0, 0, 0); } }
.LBB0_130:
	s_waitcnt vmcnt(2)
	v_exp_f32_e32 v208, v114
	v_exp_f32_e32 v209, v115
	v_exp_f32_e32 v210, v116
	v_exp_f32_e32 v211, v117
	v_exp_f32_e32 v212, v118
	v_exp_f32_e32 v213, v119
	v_exp_f32_e32 v214, v120
	v_exp_f32_e32 v215, v121
	v_exp_f32_e32 v216, v122
	v_exp_f32_e32 v217, v123
	v_exp_f32_e32 v218, v124
	v_exp_f32_e32 v219, v125
	v_exp_f32_e32 v220, v126
	v_exp_f32_e32 v221, v127
	v_exp_f32_e32 v222, v128
	v_exp_f32_e32 v223, v129
	s_waitcnt vmcnt(2)
	s_barrier
	s_add_i32 s24, s15, s24
	v_add_u32_e32 v82, s23, v199
	ds_read_b128 v[172:175], v82 offset:57344
	ds_read_b128 v[82:85], v82 offset:49152
	v_add_u32_e32 v246, s23, v198
	ds_read_b128 v[238:241], v246 offset:57344
	ds_read_b128 v[242:245], v246 offset:49152
	v_add_u32_e32 v176, s23, v197
	s_add_u32 vcc_lo, s2, s74
	s_addc_u32 vcc_hi, s3, s75
	s_add_i32 m0, s24, 0xc000
	v_lshl_add_u64 v[250:251], v[168:169], 0, vcc
	global_load_lds_dwordx4 v[250:251], off
	v_exp_f32_e32 v177, v103
	v_exp_f32_e32 v224, v108
	v_exp_f32_e32 v225, v109
	s_waitcnt lgkmcnt(2)
	v_mfma_f32_32x32x16_bf16 v[114:129], v[82:85], v[158:161], v[66:81]
	v_exp_f32_e32 v226, v110
	v_exp_f32_e32 v227, v111
	v_exp_f32_e32 v112, v112
	v_exp_f32_e32 v113, v113
	v_mfma_f32_32x32x16_bf16 v[82:97], v[172:175], v[158:161], v[66:81]
	ds_read_b128 v[172:175], v176 offset:57344
	ds_read_b128 v[204:207], v176 offset:49152
	v_add_u32_e32 v176, s23, v196
	s_add_u32 vcc_lo, s2, s74
	s_addc_u32 vcc_hi, s3, s75
	s_add_i32 m0, s24, 0xc400
	v_lshl_add_u64 v[250:251], v[170:171], 0, vcc
	global_load_lds_dwordx4 v[250:251], off
	s_waitcnt lgkmcnt(2)
	v_mfma_f32_32x32x16_bf16 v[82:97], v[238:241], v[154:157], v[82:97]
	v_mfma_f32_32x32x16_bf16 v[114:129], v[242:245], v[154:157], v[114:129]
	ds_read_b128 v[238:241], v176 offset:57344
	ds_read_b128 v[242:245], v176 offset:49152
	v_add_u32_e32 v176, s23, v195
	s_add_u32 vcc_lo, s2, 0x1c421600
	s_addc_u32 vcc_hi, s3, 0
	s_mov_b32 m0, s24
	v_lshl_add_u64 v[250:251], v[0:1], 0, vcc
	global_load_lds_dwordx4 v[250:251], off
	s_waitcnt lgkmcnt(2)
	v_mfma_f32_32x32x16_bf16 v[82:97], v[172:175], v[150:153], v[82:97]
	v_mfma_f32_32x32x16_bf16 v[114:129], v[204:207], v[150:153], v[114:129]
	ds_read_b128 v[172:175], v176 offset:57344
	ds_read_b128 v[204:207], v176 offset:49152
	v_add_u32_e32 v176, s23, v183
	s_add_u32 vcc_lo, s2, 0x1c421680
	s_addc_u32 vcc_hi, s3, 0
	s_add_i32 m0, s24, 0x400
	v_lshl_add_u64 v[250:251], v[0:1], 0, vcc
	global_load_lds_dwordx4 v[250:251], off
	s_waitcnt lgkmcnt(2)
	v_mfma_f32_32x32x16_bf16 v[82:97], v[238:241], v[146:149], v[82:97]
	v_mfma_f32_32x32x16_bf16 v[114:129], v[242:245], v[146:149], v[114:129]
	ds_read_b128 v[238:241], v176 offset:57344
	ds_read_b128 v[242:245], v176 offset:49152
	v_add_u32_e32 v176, s23, v193
	s_waitcnt lgkmcnt(2)
	v_mfma_f32_32x32x16_bf16 v[82:97], v[172:175], v[142:145], v[82:97]
	v_mfma_f32_32x32x16_bf16 v[114:129], v[204:207], v[142:145], v[114:129]
	ds_read_b128 v[172:175], v176 offset:57344
	ds_read_b128 v[204:207], v176 offset:49152
	v_add_u32_e32 v176, s23, v194
	s_waitcnt lgkmcnt(2)
	v_mfma_f32_32x32x16_bf16 v[82:97], v[238:241], v[138:141], v[82:97]
	v_mfma_f32_32x32x16_bf16 v[114:129], v[242:245], v[138:141], v[114:129]
	ds_read_b128 v[238:241], v176 offset:57344
	ds_read_b128 v[242:245], v176 offset:49152
	s_waitcnt lgkmcnt(2)
	v_mfma_f32_32x32x16_bf16 v[82:97], v[172:175], v[134:137], v[82:97]
	v_mfma_f32_32x32x16_bf16 v[114:129], v[204:207], v[134:137], v[114:129]
	v_exp_f32_e32 v176, v102
	s_waitcnt lgkmcnt(0)
	v_mfma_f32_32x32x16_bf16 v[82:97], v[238:241], v[130:133], v[82:97]
	v_exp_f32_e32 v172, v98
	v_add_f32_e32 v98, 0, v208
	v_add_f32_e32 v98, v209, v98
	v_add_f32_e32 v98, v210, v98
	v_add_f32_e32 v98, v211, v98
	v_add_f32_e32 v98, v212, v98
	v_add_f32_e32 v98, v213, v98
	v_add_f32_e32 v98, v214, v98
	v_add_f32_e32 v98, v215, v98
	v_add_f32_e32 v98, v216, v98
	v_add_f32_e32 v98, v217, v98
	v_add_f32_e32 v98, v218, v98
	v_add_f32_e32 v98, v219, v98
	v_add_f32_e32 v98, v220, v98
	v_exp_f32_e32 v173, v99
	v_add_f32_e32 v98, v221, v98
	v_exp_f32_e32 v174, v100
	v_add_f32_e32 v98, v222, v98
	v_exp_f32_e32 v175, v101
	v_add_f32_e32 v98, v223, v98
	v_add_f32_e32 v98, v172, v98
	v_add_f32_e32 v98, v173, v98
	v_mfma_f32_32x32x16_bf16 v[114:129], v[242:245], v[130:133], v[114:129]
	v_exp_f32_e32 v204, v104
	v_add_f32_e32 v98, v174, v98
	v_exp_f32_e32 v205, v105
	v_add_f32_e32 v98, v175, v98
	v_exp_f32_e32 v206, v106
	v_add_f32_e32 v98, v176, v98
	v_exp_f32_e32 v207, v107
	v_add_f32_e32 v98, v177, v98
	v_add_f32_e32 v98, v204, v98
	v_add_f32_e32 v98, v205, v98
	v_add_f32_e32 v98, v206, v98
	v_add_f32_e32 v98, v207, v98
	v_add_f32_e32 v98, v224, v98
	v_add_f32_e32 v98, v225, v98
	v_add_f32_e32 v98, v226, v98
	v_add_f32_e32 v98, v227, v98
	v_add_f32_e32 v98, v112, v98
	v_cvt_pk_bf16_f32 v100, v208, v209
	v_cvt_pk_bf16_f32 v101, v210, v211
	v_cvt_pk_bf16_f32 v102, v212, v213
	v_cvt_pk_bf16_f32 v103, v214, v215
	v_cvt_pk_bf16_f32 v104, v216, v217
	v_cvt_pk_bf16_f32 v105, v218, v219
	v_cvt_pk_bf16_f32 v106, v220, v221
	v_cvt_pk_bf16_f32 v107, v222, v223
	v_cvt_pk_bf16_f32 v108, v172, v173
	v_cvt_pk_bf16_f32 v109, v174, v175
	v_cvt_pk_bf16_f32 v110, v176, v177
	v_cvt_pk_bf16_f32 v111, v204, v205
	v_cvt_pk_bf16_f32 v172, v206, v207
	v_cvt_pk_bf16_f32 v173, v224, v225
	v_cvt_pk_bf16_f32 v174, v226, v227
	v_cvt_pk_bf16_f32 v175, v112, v113
	v_add_u32_e32 v112, s19, v182
	ds_read_b64_tr_b16 v[204:205], v112 offset:0
	ds_read_b64_tr_b16 v[206:207], v112 offset:0x800
	ds_read_b64_tr_b16 v[208:209], v112 offset:0x1000
	ds_read_b64_tr_b16 v[210:211], v112 offset:0x1800
	ds_read_b64_tr_b16 v[212:213], v112 offset:0x2000
	ds_read_b64_tr_b16 v[214:215], v112 offset:0x2800
	ds_read_b64_tr_b16 v[216:217], v112 offset:0x3000
	ds_read_b64_tr_b16 v[218:219], v112 offset:0x3800
	v_add_f32_e32 v98, v113, v98
	s_waitcnt lgkmcnt(0)
; #define SBAR() __builtin_amdgcn_sched_barrier(0)
; __device__ __forceinline__ float max3f(float a, float b, float c) { return __builtin_fmaxf(__builtin_fmaxf(a, b), c); }
; template <bool FIRST, bool MLA>
; __device__ __forceinline__ void partialSM(f32x16& p0, f32x16& p1, f32x16& negm, float& m_reg, float& alpha) {
;   float a = max3f(p0[0], p0[1], p1[0]), b = max3f(p0[2], p0[3], p1[1]); a = max3f(a, p1[2], p1[3]);
; #pragma unroll
;   for (int r = 4; r < 16; r += 4) { a = max3f(a, p0[r], p0[r + 1]); b = max3f(b, p0[r + 2], p0[r + 3]); a = max3f(a, p1[r], p1[r + 1]); b = max3f(b, p1[r + 2], p1[r + 3]); }
;   float pmax = fmaxf(a, b);
;   { auto rr = __builtin_amdgcn_permlane32_swap(__float_as_uint(pmax), __float_as_uint(pmax), false, false);
;     pmax = fmaxf(__uint_as_float(rr[0]), __uint_as_float(rr[1])); }
; template <int D0> __device__ __forceinline__ void pv_one(f32x16& od, int vb, bf16x8 pa0, bf16x8 pa1, bf16x8 pa2, bf16x8 pa3) {
;   const s16x4 l0 = tr_read<v_rd_off(D0, 0, 0)>(vb), h0 = tr_read<v_rd_off(D0, 0, 1)>(vb), l1 = tr_read<v_rd_off(D0, 1, 0)>(vb), h1 = tr_read<v_rd_off(D0, 1, 1)>(vb);
;   const s16x4 l2 = tr_read<v_rd_off(D0, 2, 0)>(vb), h2 = tr_read<v_rd_off(D0, 2, 1)>(vb), l3 = tr_read<v_rd_off(D0, 3, 0)>(vb), h3 = tr_read<v_rd_off(D0, 3, 1)>(vb);
;   asm volatile("s_waitcnt lgkmcnt(0)" ::: "memory"); SBAR();
;     ...
;   od = __builtin_amdgcn_mfma_f32_32x32x16_bf16(pa0, PK(l0, h0), od, 0, 0, 0);
;   od = __builtin_amdgcn_mfma_f32_32x32x16_bf16(pa1, PK(l1, h1), od, 0, 0, 0);
;   od = __builtin_amdgcn_mfma_f32_32x32x16_bf16(pa2, PK(l2, h2), od, 0, 0, 0);
;   od = __builtin_amdgcn_mfma_f32_32x32x16_bf16(pa3, PK(l3, h3), od, 0, 0, 0);
;     ...
; }
; __device__ __forceinline__ void pv_d0(f32x16* o, int vb, bf16x8 pa0, bf16x8 pa1, bf16x8 pa2, bf16x8 pa3) {
;   pv_one<0>(o[0], vb, pa0, pa1, pa2, pa3); pv_one<1>(o[1], vb, pa0, pa1, pa2, pa3); pv_one<2>(o[2], vb, pa0, pa1, pa2, pa3); pv_one<3>(o[3], vb, pa0, pa1, pa2, pa3);
; }
	v_mov_b32_e32 v99, v98
	s_nop 1
	v_permlane32_swap_b32_e32 v98, v99
	v_permlane32_swap_b32_e32 v100, v102
	v_permlane32_swap_b32_e32 v172, v174
	v_permlane32_swap_b32_e32 v101, v103
	v_permlane32_swap_b32_e32 v104, v106
	v_permlane32_swap_b32_e32 v105, v107
	v_permlane32_swap_b32_e32 v108, v110
	v_permlane32_swap_b32_e32 v109, v111
	v_permlane32_swap_b32_e32 v173, v175
	v_mfma_f32_32x32x16_bf16 v[2:17], v[100:103], v[204:207], v[2:17]
	ds_read_b64_tr_b16 v[204:205], v112 offset:0x200
	ds_read_b64_tr_b16 v[206:207], v112 offset:0xa00
	v_mfma_f32_32x32x16_bf16 v[2:17], v[104:107], v[208:211], v[2:17]
	ds_read_b64_tr_b16 v[208:209], v112 offset:0x1200
	ds_read_b64_tr_b16 v[210:211], v112 offset:0x1a00
	v_mfma_f32_32x32x16_bf16 v[2:17], v[108:111], v[212:215], v[2:17]
	ds_read_b64_tr_b16 v[212:213], v112 offset:0x2200
	ds_read_b64_tr_b16 v[214:215], v112 offset:0x2a00
	v_mfma_f32_32x32x16_bf16 v[2:17], v[172:175], v[216:219], v[2:17]
	ds_read_b64_tr_b16 v[216:217], v112 offset:0x3200
	ds_read_b64_tr_b16 v[218:219], v112 offset:0x3a00
	s_waitcnt lgkmcnt(0)
	v_mfma_f32_32x32x16_bf16 v[50:65], v[100:103], v[204:207], v[50:65]
	ds_read_b64_tr_b16 v[204:205], v112 offset:0x400
	ds_read_b64_tr_b16 v[206:207], v112 offset:0xc00
	v_mfma_f32_32x32x16_bf16 v[50:65], v[104:107], v[208:211], v[50:65]
	ds_read_b64_tr_b16 v[208:209], v112 offset:0x1400
	ds_read_b64_tr_b16 v[210:211], v112 offset:0x1c00
	v_mfma_f32_32x32x16_bf16 v[50:65], v[108:111], v[212:215], v[50:65]
	ds_read_b64_tr_b16 v[212:213], v112 offset:0x2400
	ds_read_b64_tr_b16 v[214:215], v112 offset:0x2c00
	v_mfma_f32_32x32x16_bf16 v[50:65], v[172:175], v[216:219], v[50:65]
	ds_read_b64_tr_b16 v[216:217], v112 offset:0x3400
	ds_read_b64_tr_b16 v[218:219], v112 offset:0x3c00
	s_waitcnt lgkmcnt(0)
	v_mfma_f32_32x32x16_bf16 v[34:49], v[100:103], v[204:207], v[34:49]
	ds_read_b64_tr_b16 v[204:205], v112 offset:0x600
	ds_read_b64_tr_b16 v[206:207], v112 offset:0xe00
	v_mfma_f32_32x32x16_bf16 v[34:49], v[104:107], v[208:211], v[34:49]
	ds_read_b64_tr_b16 v[208:209], v112 offset:0x1600
	ds_read_b64_tr_b16 v[210:211], v112 offset:0x1e00
	v_mfma_f32_32x32x16_bf16 v[34:49], v[108:111], v[212:215], v[34:49]
	ds_read_b64_tr_b16 v[212:213], v112 offset:0x2600
	ds_read_b64_tr_b16 v[214:215], v112 offset:0x2e00
	v_mfma_f32_32x32x16_bf16 v[34:49], v[172:175], v[216:219], v[34:49]
	ds_read_b64_tr_b16 v[216:217], v112 offset:0x3600
	ds_read_b64_tr_b16 v[218:219], v112 offset:0x3e00
	s_waitcnt lgkmcnt(0)
	v_mfma_f32_32x32x16_bf16 v[18:33], v[100:103], v[204:207], v[18:33]
	v_max_f32_e32 v100, v115, v115
	v_max_f32_e32 v101, v114, v114
	v_max_f32_e32 v100, v101, v100
	v_max3_f32 v101, v116, v117, v83
	v_max3_f32 v100, v100, v82, v84
	v_max3_f32 v100, v100, v85, v118
	v_max3_f32 v101, v101, v120, v121
	v_mfma_f32_32x32x16_bf16 v[18:33], v[104:107], v[208:211], v[18:33]
	v_max3_f32 v100, v100, v119, v86
	v_max3_f32 v101, v101, v88, v89
	v_max3_f32 v100, v100, v87, v122
	v_max3_f32 v101, v101, v124, v125
	v_max3_f32 v100, v100, v123, v90
	v_max3_f32 v101, v101, v92, v93
	v_max3_f32 v100, v100, v91, v126
	v_mfma_f32_32x32x16_bf16 v[18:33], v[108:111], v[212:215], v[18:33]
	v_max3_f32 v101, v101, v128, v129
	v_max3_f32 v100, v100, v127, v94
	v_max3_f32 v101, v101, v96, v97
	v_max3_f32 v100, v100, v95, v101
	v_mov_b32_e32 v101, v100
	s_nop 1
	v_permlane32_swap_b32_e32 v100, v101
	v_mfma_f32_32x32x16_bf16 v[18:33], v[172:175], v[216:219], v[18:33]
	v_max_f32_e32 v101, v101, v101
	v_max_f32_e32 v100, v100, v100
	v_max_f32_e32 v100, v100, v101
	v_cmp_lt_f32_e32 vcc, s40, v100
	v_mov_b32_e32 v172, 1.0
	s_cbranch_vccnz .LBB0_138
	v_cmp_gt_f32_e32 vcc, 1.0, v172
	s_cbranch_vccz .LBB0_135

; #define SBAR() __builtin_amdgcn_sched_barrier(0)
; #define WAIT_BAR() do { asm volatile("s_waitcnt vmcnt(0)" ::: "memory"); __syncthreads(); } while (0)
; #define RESC(a) do { if (__any((a) < 1.f)) { if (hi == 0) al_l[r32] = (a); asm volatile("s_waitcnt lgkmcnt(0)" ::: "memory"); \
;     _Pragma("unroll") for (int d = 0; d < 4; ++d) _Pragma("unroll") for (int r = 0; r < 16; ++r) o[d][r] *= al_l[crow(r, hi)]; } } while (0)
; #define ROT() do { const int t_ = s_prev; s_prev = s_cur; s_cur = s_next; s_next = t_; } while (0)
; template <bool MLA> ...
;     ...
;   for (int j = 1; j + 1 < NT; j += 2) {
;     SBAR(); DMA_TILE(j + 1, s_next); SBAR();
;     qkt<MLA>(pB0, pB1, K_lds + s_cur * SHM_K, KR_lds + s_cur * SHM_KR, qr, qrl, negm, r32, hi);
;     finishSM(pA0, pA1, alA, l_reg, pa0, pa1, pa2, pa3);
;     pv_d0(o, vb0 + s_prev * SHM_V, pa0, pa1, pa2, pa3); partialSM<false, false>(pB0, pB1, negm, m_reg, alB);
;     RESC(alB); WAIT_BAR(); ROT();
;     SBAR(); DMA_TILE(j + 2, s_next); SBAR();
;     qkt<MLA>(pA0, pA1, K_lds + s_cur * SHM_K, KR_lds + s_cur * SHM_KR, qr, qrl, negm, r32, hi);
;     finishSM(pB0, pB1, alB, l_reg, pa0, pa1, pa2, pa3);
;     pv_d0(o, vb0 + s_prev * SHM_V, pa0, pa1, pa2, pa3); partialSM<false, false>(pA0, pA1, negm, m_reg, alA);
;     RESC(alA); WAIT_BAR(); ROT();
;   }
.LBB0_135:
	v_exp_f32_e32 v217, v114
	v_exp_f32_e32 v219, v115
	v_exp_f32_e32 v215, v116
	v_exp_f32_e32 v218, v117
	v_exp_f32_e32 v214, v118
	v_exp_f32_e32 v216, v119
	v_exp_f32_e32 v212, v120
	v_exp_f32_e32 v213, v121
	v_exp_f32_e32 v209, v122
	v_exp_f32_e32 v211, v123
	v_exp_f32_e32 v208, v124
	v_exp_f32_e32 v210, v125
	v_exp_f32_e32 v205, v126
	v_exp_f32_e32 v207, v127
	v_exp_f32_e32 v204, v128
	v_exp_f32_e32 v206, v129
	s_add_i32 s18, s18, 2
	v_add_f32_e32 v100, v201, v202
	s_waitcnt vmcnt(2)
	s_add_u32 s2, s2, 0xc0000
	v_fmac_f32_e32 v100, v200, v180
	v_add_f32_e32 v180, v98, v99
	s_addc_u32 s3, s3, 0
	v_fmac_f32_e32 v180, v100, v203
	s_cmpk_gt_u32 s18, 0x7c
	s_waitcnt vmcnt(2)
	s_barrier
	s_cbranch_scc1 .LBB0_139
	s_mov_b32 s23, s17
	s_mov_b32 s17, s13
	v_mov_b32_e32 v200, v172
	s_branch .LBB0_125

; #define SBAR() __builtin_amdgcn_sched_barrier(0)
; __device__ __forceinline__ void finishSM(f32x16& p0, f32x16& p1, float alpha, float& l_reg, bf16x8& pa0, bf16x8& pa1, bf16x8& pa2, bf16x8& pa3) {
; #pragma unroll
;   for (int r = 0; r < 16; ++r) p1[r] = __builtin_amdgcn_exp2f(p1[r]);
;   float ps = 0;
; #pragma unroll
;   for (int r = 0; r < 16; ++r) ps += p0[r];
; #pragma unroll
;   for (int r = 0; r < 16; ++r) ps += p1[r];
;   { auto rr = __builtin_amdgcn_permlane32_swap(__float_as_uint(ps), __float_as_uint(ps), false, false);
;     ps = __uint_as_float(rr[0]) + __uint_as_float(rr[1]); }
;   l_reg = l_reg * alpha + ps;
;     ...
;   PK4(p0, 0, pa0); PK4(p0, 8, pa1); PK4(p1, 0, pa2); PK4(p1, 8, pa3);
;     ...
; }
; template <bool MLA>
; __device__ __forceinline__ void qkt(f32x16& p0, f32x16& p1, const char* Ks, const char* KRs, const bf16x8* qr, const char* qrl, const f32x16& negm, int r32, int hi) {
; #pragma unroll
;   for (int d0 = 0; d0 < 8; ++d0) { int cb = (d0 * 16 + hi * 8) * 2;
;     bf16x8 b0 = *reinterpret_cast<const bf16x8*>(Ks + KSWZ(r32, cb));
;     bf16x8 b1 = *reinterpret_cast<const bf16x8*>(Ks + KSWZ(32 + r32, cb));
;     if (d0 == 0) { p0 = __builtin_amdgcn_mfma_f32_32x32x16_bf16(b0, qr[0], negm, 0, 0, 0); p1 = __builtin_amdgcn_mfma_f32_32x32x16_bf16(b1, qr[0], negm, 0, 0, 0); }
;     else { p0 = __builtin_amdgcn_mfma_f32_32x32x16_bf16(b0, qr[d0], p0, 0, 0, 0); p1 = __builtin_amdgcn_mfma_f32_32x32x16_bf16(b1, qr[d0], p1, 0, 0, 0); } }
; template <bool MLA> ...
;     ...
;   SBAR(); qkt<MLA>(pB0, pB1, K_lds + s_cur * SHM_K, KR_lds + s_cur * SHM_KR, qr, qrl, negm, r32, hi);
;   finishSM(pA0, pA1, alA, l_reg, pa0, pa1, pa2, pa3); SBAR();
;   pv_d0(o, vb0 + s_prev * SHM_V, pa0, pa1, pa2, pa3); partialSM<false, false>(pB0, pB1, negm, m_reg, alB);
.LBB0_139:
	s_waitcnt vmcnt(0)
	s_barrier
	s_add_i32 s2, 0, 0x10000
	v_add_u32_e32 v0, s2, v199
	ds_read_b128 v[168:171], v0 offset:8192
	ds_read_b128 v[98:101], v0
	v_add_u32_e32 v0, s2, v198
	v_exp_f32_e32 v83, v83
	v_exp_f32_e32 v96, v96
	v_exp_f32_e32 v97, v97
	s_waitcnt lgkmcnt(0)
	v_mfma_f32_32x32x16_bf16 v[114:129], v[98:101], v[158:161], v[66:81]
	v_mfma_f32_32x32x16_bf16 v[98:113], v[168:171], v[158:161], v[66:81]
	ds_read_b128 v[158:161], v0 offset:8192
	ds_read_b128 v[168:171], v0
	v_add_u32_e32 v0, s2, v197
	s_waitcnt lgkmcnt(0)
	v_mfma_f32_32x32x16_bf16 v[114:129], v[168:171], v[154:157], v[114:129]
	v_mfma_f32_32x32x16_bf16 v[98:113], v[158:161], v[154:157], v[98:113]
	ds_read_b128 v[154:157], v0 offset:8192
	ds_read_b128 v[158:161], v0
	v_add_u32_e32 v0, s2, v196
	s_waitcnt lgkmcnt(0)
	v_mfma_f32_32x32x16_bf16 v[114:129], v[158:161], v[150:153], v[114:129]
	v_mfma_f32_32x32x16_bf16 v[98:113], v[154:157], v[150:153], v[98:113]
	ds_read_b128 v[150:153], v0 offset:8192
	ds_read_b128 v[154:157], v0
	v_add_u32_e32 v0, s2, v195
	s_waitcnt lgkmcnt(0)
	v_mfma_f32_32x32x16_bf16 v[114:129], v[154:157], v[146:149], v[114:129]
	v_mfma_f32_32x32x16_bf16 v[98:113], v[150:153], v[146:149], v[98:113]
	ds_read_b128 v[146:149], v0 offset:8192
	ds_read_b128 v[150:153], v0
	v_add_u32_e32 v0, s2, v183
	s_waitcnt lgkmcnt(0)
	v_mfma_f32_32x32x16_bf16 v[114:129], v[150:153], v[142:145], v[114:129]
	v_mfma_f32_32x32x16_bf16 v[98:113], v[146:149], v[142:145], v[98:113]
	ds_read_b128 v[142:145], v0 offset:8192
	ds_read_b128 v[146:149], v0
	v_add_u32_e32 v0, s2, v193
	s_waitcnt lgkmcnt(0)
	v_mfma_f32_32x32x16_bf16 v[114:129], v[146:149], v[138:141], v[114:129]
	v_mfma_f32_32x32x16_bf16 v[98:113], v[142:145], v[138:141], v[98:113]
	ds_read_b128 v[138:141], v0 offset:8192
	ds_read_b128 v[142:145], v0
	v_add_u32_e32 v0, s2, v194
	s_waitcnt lgkmcnt(0)
	v_mfma_f32_32x32x16_bf16 v[114:129], v[142:145], v[134:137], v[114:129]
	v_exp_f32_e32 v142, v95
	v_mfma_f32_32x32x16_bf16 v[98:113], v[138:141], v[134:137], v[98:113]
	ds_read_b128 v[134:137], v0 offset:8192
	ds_read_b128 v[138:141], v0
	v_add_f32_e32 v0, 0, v217
	v_add_f32_e32 v0, v219, v0
	v_add_f32_e32 v0, v215, v0
	v_add_f32_e32 v0, v218, v0
	v_add_f32_e32 v0, v214, v0
	v_add_f32_e32 v0, v216, v0
	v_add_f32_e32 v0, v212, v0
	v_add_f32_e32 v0, v213, v0
	v_add_f32_e32 v0, v209, v0
	v_add_f32_e32 v0, v211, v0
	v_add_f32_e32 v0, v208, v0
	v_add_f32_e32 v0, v210, v0
	s_waitcnt lgkmcnt(0)
	v_mfma_f32_32x32x16_bf16 v[114:129], v[138:141], v[130:133], v[114:129]
	v_add_f32_e32 v0, v205, v0
	v_add_f32_e32 v0, v207, v0
	v_add_f32_e32 v0, v204, v0
	v_add_f32_e32 v0, v206, v0
	v_exp_f32_e32 v138, v91
	v_exp_f32_e32 v139, v92
	v_exp_f32_e32 v140, v93
	v_mfma_f32_32x32x16_bf16 v[98:113], v[134:137], v[130:133], v[98:113]
	v_exp_f32_e32 v130, v82
	v_exp_f32_e32 v131, v84
	v_exp_f32_e32 v132, v85
	v_exp_f32_e32 v133, v86
	v_add_f32_e32 v0, v130, v0
	v_exp_f32_e32 v134, v87
	v_add_f32_e32 v0, v83, v0
	v_exp_f32_e32 v135, v88
	v_add_f32_e32 v0, v131, v0
	v_exp_f32_e32 v136, v89
	v_add_f32_e32 v0, v132, v0
	v_exp_f32_e32 v137, v90
	v_add_f32_e32 v0, v133, v0
	v_add_f32_e32 v0, v134, v0
	v_add_f32_e32 v0, v135, v0
	v_add_f32_e32 v0, v136, v0
	v_exp_f32_e32 v141, v94
	v_add_f32_e32 v0, v137, v0
	v_add_f32_e32 v0, v138, v0
	v_add_f32_e32 v0, v139, v0
	v_add_f32_e32 v0, v140, v0
	v_add_f32_e32 v0, v141, v0
	v_add_f32_e32 v0, v142, v0
	v_add_f32_e32 v0, v96, v0
	v_add_f32_e32 v0, v97, v0
	v_mov_b32_e32 v82, v0
	v_cvt_pk_bf16_f32 v84, v217, v219
	v_cvt_pk_bf16_f32 v85, v215, v218
	v_cvt_pk_bf16_f32 v86, v214, v216
	s_nop 1
	v_permlane32_swap_b32_e32 v0, v82
	v_cvt_pk_bf16_f32 v87, v212, v213
	v_permlane32_swap_b32_e32 v84, v86
	v_cvt_pk_bf16_f32 v88, v209, v211
	v_cvt_pk_bf16_f32 v89, v208, v210
	v_cvt_pk_bf16_f32 v90, v205, v207
	v_cvt_pk_bf16_f32 v91, v204, v206
	v_cvt_pk_bf16_f32 v92, v130, v83
	v_cvt_pk_bf16_f32 v93, v131, v132
	v_cvt_pk_bf16_f32 v94, v133, v134
	v_cvt_pk_bf16_f32 v95, v135, v136
	v_cvt_pk_bf16_f32 v130, v137, v138
	v_cvt_pk_bf16_f32 v131, v139, v140
	v_cvt_pk_bf16_f32 v132, v141, v142
	v_cvt_pk_bf16_f32 v133, v96, v97
	v_permlane32_swap_b32_e32 v85, v87
	v_permlane32_swap_b32_e32 v88, v90
	v_permlane32_swap_b32_e32 v89, v91
	v_permlane32_swap_b32_e32 v92, v94
	v_permlane32_swap_b32_e32 v93, v95
	v_permlane32_swap_b32_e32 v130, v132
	v_permlane32_swap_b32_e32 v131, v133
	ds_read_b64_tr_b16 v[134:135], v182 offset:0
	ds_read_b64_tr_b16 v[136:137], v182 offset:0x800
	ds_read_b64_tr_b16 v[138:139], v182 offset:0x1000
	ds_read_b64_tr_b16 v[140:141], v182 offset:0x1800
	ds_read_b64_tr_b16 v[142:143], v182 offset:0x2000
	ds_read_b64_tr_b16 v[144:145], v182 offset:0x2800
	ds_read_b64_tr_b16 v[146:147], v182 offset:0x3000
	ds_read_b64_tr_b16 v[148:149], v182 offset:0x3800
	s_waitcnt lgkmcnt(0)
; #define SBAR() __builtin_amdgcn_sched_barrier(0)
; __device__ __forceinline__ float max3f(float a, float b, float c) { return __builtin_fmaxf(__builtin_fmaxf(a, b), c); }
; template <bool FIRST, bool MLA>
; __device__ __forceinline__ void partialSM(f32x16& p0, f32x16& p1, f32x16& negm, float& m_reg, float& alpha) {
;   float a = max3f(p0[0], p0[1], p1[0]), b = max3f(p0[2], p0[3], p1[1]); a = max3f(a, p1[2], p1[3]);
; #pragma unroll
;   for (int r = 4; r < 16; r += 4) { a = max3f(a, p0[r], p0[r + 1]); b = max3f(b, p0[r + 2], p0[r + 3]); a = max3f(a, p1[r], p1[r + 1]); b = max3f(b, p1[r + 2], p1[r + 3]); }
;   float pmax = fmaxf(a, b);
;   { auto rr = __builtin_amdgcn_permlane32_swap(__float_as_uint(pmax), __float_as_uint(pmax), false, false);
;     pmax = fmaxf(__uint_as_float(rr[0]), __uint_as_float(rr[1])); }
; template <int D0> __device__ __forceinline__ void pv_one(f32x16& od, int vb, bf16x8 pa0, bf16x8 pa1, bf16x8 pa2, bf16x8 pa3) {
;   const s16x4 l0 = tr_read<v_rd_off(D0, 0, 0)>(vb), h0 = tr_read<v_rd_off(D0, 0, 1)>(vb), l1 = tr_read<v_rd_off(D0, 1, 0)>(vb), h1 = tr_read<v_rd_off(D0, 1, 1)>(vb);
;   const s16x4 l2 = tr_read<v_rd_off(D0, 2, 0)>(vb), h2 = tr_read<v_rd_off(D0, 2, 1)>(vb), l3 = tr_read<v_rd_off(D0, 3, 0)>(vb), h3 = tr_read<v_rd_off(D0, 3, 1)>(vb);
;   asm volatile("s_waitcnt lgkmcnt(0)" ::: "memory"); SBAR();
;     ...
;   od = __builtin_amdgcn_mfma_f32_32x32x16_bf16(pa0, PK(l0, h0), od, 0, 0, 0);
;   od = __builtin_amdgcn_mfma_f32_32x32x16_bf16(pa1, PK(l1, h1), od, 0, 0, 0);
;   od = __builtin_amdgcn_mfma_f32_32x32x16_bf16(pa2, PK(l2, h2), od, 0, 0, 0);
;   od = __builtin_amdgcn_mfma_f32_32x32x16_bf16(pa3, PK(l3, h3), od, 0, 0, 0);
;     ...
; }
; __device__ __forceinline__ void pv_d0(f32x16* o, int vb, bf16x8 pa0, bf16x8 pa1, bf16x8 pa2, bf16x8 pa3) {
;   pv_one<0>(o[0], vb, pa0, pa1, pa2, pa3); pv_one<1>(o[1], vb, pa0, pa1, pa2, pa3); pv_one<2>(o[2], vb, pa0, pa1, pa2, pa3); pv_one<3>(o[3], vb, pa0, pa1, pa2, pa3);
; }
	s_nop 0
	v_mfma_f32_32x32x16_bf16 v[2:17], v[84:87], v[134:137], v[2:17]
	ds_read_b64_tr_b16 v[134:135], v182 offset:0x200
	ds_read_b64_tr_b16 v[136:137], v182 offset:0xa00
	v_mfma_f32_32x32x16_bf16 v[2:17], v[88:91], v[138:141], v[2:17]
	ds_read_b64_tr_b16 v[138:139], v182 offset:0x1200
	ds_read_b64_tr_b16 v[140:141], v182 offset:0x1a00
	v_mfma_f32_32x32x16_bf16 v[2:17], v[92:95], v[142:145], v[2:17]
	ds_read_b64_tr_b16 v[142:143], v182 offset:0x2200
	ds_read_b64_tr_b16 v[144:145], v182 offset:0x2a00
	v_mfma_f32_32x32x16_bf16 v[2:17], v[130:133], v[146:149], v[2:17]
	ds_read_b64_tr_b16 v[146:147], v182 offset:0x3200
	ds_read_b64_tr_b16 v[148:149], v182 offset:0x3a00
	s_waitcnt lgkmcnt(0)
	v_mfma_f32_32x32x16_bf16 v[50:65], v[84:87], v[134:137], v[50:65]
	ds_read_b64_tr_b16 v[134:135], v182 offset:0x400
	ds_read_b64_tr_b16 v[136:137], v182 offset:0xc00
	v_mfma_f32_32x32x16_bf16 v[50:65], v[88:91], v[138:141], v[50:65]
	ds_read_b64_tr_b16 v[138:139], v182 offset:0x1400
	ds_read_b64_tr_b16 v[140:141], v182 offset:0x1c00
	v_mfma_f32_32x32x16_bf16 v[50:65], v[92:95], v[142:145], v[50:65]
	ds_read_b64_tr_b16 v[142:143], v182 offset:0x2400
	ds_read_b64_tr_b16 v[144:145], v182 offset:0x2c00
	v_mfma_f32_32x32x16_bf16 v[50:65], v[130:133], v[146:149], v[50:65]
	ds_read_b64_tr_b16 v[146:147], v182 offset:0x3400
	ds_read_b64_tr_b16 v[148:149], v182 offset:0x3c00
	s_waitcnt lgkmcnt(0)
	v_mfma_f32_32x32x16_bf16 v[34:49], v[84:87], v[134:137], v[34:49]
	ds_read_b64_tr_b16 v[134:135], v182 offset:0x600
	ds_read_b64_tr_b16 v[136:137], v182 offset:0xe00
	v_mfma_f32_32x32x16_bf16 v[34:49], v[88:91], v[138:141], v[34:49]
	ds_read_b64_tr_b16 v[138:139], v182 offset:0x1600
	ds_read_b64_tr_b16 v[140:141], v182 offset:0x1e00
	v_mfma_f32_32x32x16_bf16 v[34:49], v[92:95], v[142:145], v[34:49]
	ds_read_b64_tr_b16 v[142:143], v182 offset:0x2600
	ds_read_b64_tr_b16 v[144:145], v182 offset:0x2e00
	v_mfma_f32_32x32x16_bf16 v[34:49], v[130:133], v[146:149], v[34:49]
	ds_read_b64_tr_b16 v[146:147], v182 offset:0x3600
	ds_read_b64_tr_b16 v[148:149], v182 offset:0x3e00
	s_waitcnt lgkmcnt(0)
	v_mfma_f32_32x32x16_bf16 v[18:33], v[84:87], v[134:137], v[18:33]
	v_max_f32_e32 v83, v115, v115
	v_max_f32_e32 v84, v114, v114
	v_max_f32_e32 v83, v84, v83
	v_max3_f32 v84, v116, v117, v99
	v_max3_f32 v83, v83, v98, v100
	v_max3_f32 v83, v83, v101, v118
	v_max3_f32 v84, v84, v120, v121
	v_mfma_f32_32x32x16_bf16 v[18:33], v[88:91], v[138:141], v[18:33]
	v_max3_f32 v83, v83, v119, v102
	v_max3_f32 v84, v84, v104, v105
	v_max3_f32 v83, v83, v103, v122
	v_max3_f32 v84, v84, v124, v125
	v_max3_f32 v83, v83, v123, v106
	v_max3_f32 v84, v84, v108, v109
	v_max3_f32 v83, v83, v107, v126
	v_mfma_f32_32x32x16_bf16 v[18:33], v[92:95], v[142:145], v[18:33]
	v_max3_f32 v84, v84, v128, v129
	v_max3_f32 v83, v83, v127, v110
	v_max3_f32 v84, v84, v112, v113
	v_max3_f32 v83, v83, v111, v84
	v_mov_b32_e32 v84, v83
	s_nop 1
	v_permlane32_swap_b32_e32 v83, v84
	v_mfma_f32_32x32x16_bf16 v[18:33], v[130:133], v[146:149], v[18:33]
	v_max_f32_e32 v84, v84, v84
	v_max_f32_e32 v83, v83, v83
	v_max_f32_e32 v84, v83, v84
	v_cmp_lt_f32_e32 vcc, s40, v84
	v_mov_b32_e32 v83, 1.0
	s_cbranch_vccnz .LBB0_147
	v_cmp_gt_f32_e32 vcc, 1.0, v83
	s_cbranch_vccz .LBB0_144

; template <class Epi>
; __device__ __forceinline__ void gemm_phase(LAS unsigned char* lds, const Gemm g, const StaticOrder& S, const Epi& E) {
;     ...
; #pragma unroll
;         for (int a = 0; a < 2; ++a)
; #pragma unroll
;             for (int b = 0; b < 2; ++b)
; #pragma unroll
;                 for (int m = 0; m < 4; ++m)
; #pragma unroll
;                     for (int n = 0; n < 2; ++n) acc[a][b][m][n] = (f32x4){0.f, 0.f, 0.f, 0.f};
;         cur = nxt; cA = nA; cB = nB; ++ui;
.LBB0_232:
	s_add_u32 s12, s82, 0x80
	s_addc_u32 s13, s83, 0
	s_add_u32 s57, s26, 0x100
	v_mov_b64_e32 v[2:3], 0
	v_mov_b64_e32 v[4:5], 0
	v_mov_b64_e32 v[6:7], 0
	v_mov_b64_e32 v[8:9], 0
	v_mov_b64_e32 v[10:11], 0
	v_mov_b64_e32 v[12:13], 0
	v_mov_b64_e32 v[14:15], 0
	v_mov_b64_e32 v[16:17], 0
	v_mov_b64_e32 v[18:19], 0
	v_mov_b64_e32 v[20:21], 0
	v_mov_b64_e32 v[22:23], 0
	v_mov_b64_e32 v[24:25], 0
	v_mov_b64_e32 v[26:27], 0
	v_mov_b64_e32 v[28:29], 0
	v_mov_b64_e32 v[30:31], 0
	v_mov_b64_e32 v[32:33], 0
	v_mov_b64_e32 v[34:35], 0
	v_mov_b64_e32 v[36:37], 0
	v_mov_b64_e32 v[38:39], 0
	v_mov_b64_e32 v[40:41], 0
	v_mov_b64_e32 v[42:43], 0
	v_mov_b64_e32 v[44:45], 0
	v_mov_b64_e32 v[46:47], 0
	v_mov_b64_e32 v[48:49], 0
	v_mov_b64_e32 v[50:51], 0
	v_mov_b64_e32 v[52:53], 0
	v_mov_b64_e32 v[54:55], 0
	v_mov_b64_e32 v[56:57], 0
	v_mov_b64_e32 v[58:59], 0
	v_mov_b64_e32 v[60:61], 0
	v_mov_b64_e32 v[62:63], 0
	v_mov_b64_e32 v[64:65], 0
	v_mov_b64_e32 v[66:67], 0
	v_mov_b64_e32 v[68:69], 0
	v_mov_b64_e32 v[70:71], 0
	v_mov_b64_e32 v[72:73], 0
	v_mov_b64_e32 v[74:75], 0
	v_mov_b64_e32 v[76:77], 0
	v_mov_b64_e32 v[78:79], 0
	v_mov_b64_e32 v[80:81], 0
	v_mov_b64_e32 v[82:83], 0
	v_mov_b64_e32 v[84:85], 0
	v_mov_b64_e32 v[86:87], 0
	v_mov_b64_e32 v[88:89], 0
	v_mov_b64_e32 v[90:91], 0
	v_mov_b64_e32 v[92:93], 0
	v_mov_b64_e32 v[94:95], 0
	v_mov_b64_e32 v[96:97], 0
	v_mov_b64_e32 v[98:99], 0
	v_mov_b64_e32 v[100:101], 0
	v_mov_b64_e32 v[102:103], 0
	v_mov_b64_e32 v[104:105], 0
	v_mov_b64_e32 v[106:107], 0
	v_mov_b64_e32 v[108:109], 0
	v_mov_b64_e32 v[110:111], 0
	v_mov_b64_e32 v[112:113], 0
	v_mov_b64_e32 v[114:115], 0
	v_mov_b64_e32 v[116:117], 0
	v_mov_b64_e32 v[118:119], 0
	v_mov_b64_e32 v[120:121], 0
	v_mov_b64_e32 v[122:123], 0
	v_mov_b64_e32 v[124:125], 0
	v_mov_b64_e32 v[126:127], 0
	v_mov_b64_e32 v[128:129], 0
	s_addc_u32 s82, s27, 0
	s_mov_b32 s26, 0

; template <class Epi>
; __device__ __forceinline__ void gemm_phase(LAS unsigned char* lds, const Gemm g, const StaticOrder& S, const Epi& E) {
;     ...
;         const char* nA = has_next ? (const char*)g.A + PG8_AOFF(nxt) : cA; const char* nB = has_next ? (const char*)g.Bt + (size_t)nxt.pn * tstepB : cB;
;     ...
; #pragma unroll
;         for (int a = 0; a < 2; ++a)
; #pragma unroll
;             for (int b = 0; b < 2; ++b)
; #pragma unroll
;                 for (int m = 0; m < 4; ++m)
; #pragma unroll
;                     for (int n = 0; n < 2; ++n) acc[a][b][m][n] = (f32x4){0.f, 0.f, 0.f, 0.f};
;         cur = nxt; cA = nA; cB = nB; ++ui;
.LBB0_294:
	s_ashr_i32 s13, s12, 31
	s_lshl_b64 s[14:15], s[12:13], 20
	s_add_u32 s14, s82, s14
	s_addc_u32 s15, s83, s15
	s_and_b64 s[16:17], s[6:7], exec
	s_cselect_b32 s13, s15, s25
	s_cselect_b32 s43, s14, s24
	s_ashr_i32 s11, s10, 31
	s_lshl_b64 s[16:17], s[10:11], 20
	s_add_u32 s16, s2, s16
	s_addc_u32 s17, s3, s17
	s_and_b64 s[34:35], s[6:7], exec
	s_cselect_b32 s11, s17, s27
	s_cselect_b32 s46, s16, s26
	s_add_u32 s24, s24, 0x80080
	s_addc_u32 s25, s25, 0
	s_add_u32 s47, s26, 0x100
	v_mov_b64_e32 v[2:3], 0
	v_mov_b64_e32 v[4:5], 0
	v_mov_b64_e32 v[6:7], 0
	v_mov_b64_e32 v[8:9], 0
	v_mov_b64_e32 v[10:11], 0
	v_mov_b64_e32 v[12:13], 0
	v_mov_b64_e32 v[14:15], 0
	v_mov_b64_e32 v[16:17], 0
	v_mov_b64_e32 v[18:19], 0
	v_mov_b64_e32 v[20:21], 0
	v_mov_b64_e32 v[22:23], 0
	v_mov_b64_e32 v[24:25], 0
	v_mov_b64_e32 v[26:27], 0
	v_mov_b64_e32 v[28:29], 0
	v_mov_b64_e32 v[30:31], 0
	v_mov_b64_e32 v[32:33], 0
	v_mov_b64_e32 v[34:35], 0
	v_mov_b64_e32 v[36:37], 0
	v_mov_b64_e32 v[38:39], 0
	v_mov_b64_e32 v[40:41], 0
	v_mov_b64_e32 v[42:43], 0
	v_mov_b64_e32 v[44:45], 0
	v_mov_b64_e32 v[46:47], 0
	v_mov_b64_e32 v[48:49], 0
	v_mov_b64_e32 v[50:51], 0
	v_mov_b64_e32 v[52:53], 0
	v_mov_b64_e32 v[54:55], 0
	v_mov_b64_e32 v[56:57], 0
	v_mov_b64_e32 v[58:59], 0
	v_mov_b64_e32 v[60:61], 0
	v_mov_b64_e32 v[62:63], 0
	v_mov_b64_e32 v[64:65], 0
	v_mov_b64_e32 v[66:67], 0
	v_mov_b64_e32 v[68:69], 0
	v_mov_b64_e32 v[70:71], 0
	v_mov_b64_e32 v[72:73], 0
	v_mov_b64_e32 v[74:75], 0
	v_mov_b64_e32 v[76:77], 0
	v_mov_b64_e32 v[78:79], 0
	v_mov_b64_e32 v[80:81], 0
	v_mov_b64_e32 v[82:83], 0
	v_mov_b64_e32 v[84:85], 0
	v_mov_b64_e32 v[86:87], 0
	v_mov_b64_e32 v[88:89], 0
	v_mov_b64_e32 v[90:91], 0
	v_mov_b64_e32 v[92:93], 0
	v_mov_b64_e32 v[94:95], 0
	v_mov_b64_e32 v[96:97], 0
	v_mov_b64_e32 v[98:99], 0
	v_mov_b64_e32 v[100:101], 0
	v_mov_b64_e32 v[102:103], 0
	v_mov_b64_e32 v[104:105], 0
	v_mov_b64_e32 v[106:107], 0
	v_mov_b64_e32 v[108:109], 0
	v_mov_b64_e32 v[110:111], 0
	v_mov_b64_e32 v[112:113], 0
	v_mov_b64_e32 v[114:115], 0
	v_mov_b64_e32 v[116:117], 0
	v_mov_b64_e32 v[118:119], 0
	v_mov_b64_e32 v[120:121], 0
	v_mov_b64_e32 v[122:123], 0
	v_mov_b64_e32 v[124:125], 0
	v_mov_b64_e32 v[126:127], 0
	v_mov_b64_e32 v[128:129], 0
	s_waitcnt lgkmcnt(0)
	s_addc_u32 s48, s27, 0
	s_mov_b32 s49, -2
